# DIFF attention loop: PV accumulates in place, 128 phi copies (v_mov_b64) and MFMA-drain nops removed; MLA QK K-fragments prefetched
# speedup vs baseline: 1.0505x; 1.0320x over previous
; template <int MODE>
; __device__ __forceinline__ void attn_item(const Params& P, int layer, int b, int h, int map, int qb) {
;     ...
;   for (int i = 0; i < ntp; i += 2) {
;     const int base = (i & 2);
;     ATT_STEP(i, stY, base)
;     ATT_STEP(i + 1, stX, base + 1)
;     __syncthreads();
;   }
.LBB0_1249:
	v_mov_b32_e32 v228, v126
	v_mov_b32_e32 v177, v156

; #define LAS __attribute__((address_space(3)))
; __device__ __forceinline__ float max32(float v) { return __builtin_fmaxf(v, xhalf(v)); }
; __device__ __forceinline__ void softmax_tile(f32x16& s0, f32x16& s1, SM& st, float boff, ldsp_t vb, int hh, int r) {
;     ...
;   float zmax = max3f(s0[0], s0[1], s0[2]);
; #pragma unroll
;   for (int k = 0; k < 6; ++k) zmax = max3f(zmax, s0[3 + 2 * k], s0[4 + 2 * k]);
;   zmax = max3f(zmax, s0[15], s1[0]);
; #pragma unroll
;   for (int k = 0; k < 7; ++k) zmax = max3f(zmax, s1[1 + 2 * k], s1[2 + 2 * k]);
;   zmax = fmaxf(zmax, s1[15]);
; #pragma unroll
;   for (int i = 0; i < 16; ++i) { s0[i] = __builtin_amdgcn_exp2f(s0[i]); s1[i] = __builtin_amdgcn_exp2f(s1[i]); }
;   if (__any((zmax + boff > st.m + DEFER_THR) || (st.m != boff))) {
;     const float zt = max32(zmax) + boff; const bool need = zt > st.m + DEFER_THR;
;     const float mn = need ? zt : st.m, alpha = __builtin_amdgcn_exp2f(st.m - mn), f = __builtin_amdgcn_exp2f(__builtin_fminf(boff - mn, 120.f)); st.m = mn;
; #pragma unroll
;     for (int i = 0; i < 16; ++i) { s0[i] *= f; s1[i] *= f; st.o0[i] *= alpha; st.o1[i] *= alpha; }
;     st.l *= alpha;
; template <int MODE>
; __device__ __forceinline__ void attn_item(const Params& P, int layer, int b, int h, int map, int qb) {
;     ...
;   auto qk = [&](f32x16& s0, f32x16& s1, float& boff, int bufi, int t) {
;     const ldsp_t kbuf = lds + bufi * KBUF;
;     __builtin_amdgcn_s_setprio(1);
;     boff = sa.m > -1e29f ? sa.m : 0.f;
;     const float init = ((MODE == 1 && !lookf(t)) ? cfar : 0.f) - boff;
; #pragma unroll
;     for (int q = 0; q < 16; ++q) { s0[q] = init; s1[q] = init; }
; #pragma unroll
;     for (int s = 0; s < NST; ++s) {
;       const bf16x8 a0 = *(LAS const bf16x8*)(kbuf + pr * KSTR + s * 32 + hh * 16);
;       const bf16x8 a1 = *(LAS const bf16x8*)(kbuf + (32 + pr) * KSTR + s * 32 + hh * 16);
;       s0 = __builtin_amdgcn_mfma_f32_32x32x16_bf16(a0, qf[s], s0, 0, 0, 0);
;       s1 = __builtin_amdgcn_mfma_f32_32x32x16_bf16(a1, qf[s], s1, 0, 0, 0);
;     }
;     __builtin_amdgcn_sched_group_barrier(0x100, 4, 0);
; #pragma unroll
;     for (int s = 0; s < NST - 2; ++s) { __builtin_amdgcn_sched_group_barrier(0x8, 2, 0); __builtin_amdgcn_sched_group_barrier(0x100, 2, 0); }
;     __builtin_amdgcn_sched_group_barrier(0x8, 4, 0);
;     __builtin_amdgcn_s_setprio(0);
;   };
.LBB0_1251:
	s_and_b32 s78, s48, 2
	s_cmp_ge_u32 s48, s62
	s_cbranch_scc1 .LBB0_1268
	s_lshl_b32 s84, s48, 6
	s_cmp_gt_i32 s84, s37
	s_cselect_b64 s[2:3], -1, 0
	s_or_b64 s[2:3], s[2:3], s[40:41]
	s_cmp_eq_u32 s48, 0
	v_cndmask_b32_e64 v34, 0, 1, s[2:3]
	v_cndmask_b32_e64 v35, 0, 1, s[40:41]
	s_cselect_b64 s[2:3], -1, 0
	v_cndmask_b32_e64 v34, v34, v35, s[2:3]
	v_and_b32_e32 v34, 1, v34
	v_cmp_eq_u32_e32 vcc, 1, v34
	s_cbranch_vccnz .LBB0_1268
	s_sub_i32 s6, s80, s84
	s_cmpk_gt_i32 s6, 0x7f
	s_cselect_b64 s[4:5], -1, 0
	s_cmpk_lt_i32 s6, 0x80
	s_cselect_b64 s[42:43], -1, 0
	s_mul_i32 s6, s78, 0x2400
	s_add_i32 s90, s6, 0
	s_or_b64 s[6:7], s[2:3], s[42:43]
	s_or_b32 s42, s84, 63
	s_cmp_gt_i32 s42, s36
	s_cselect_b64 s[42:43], -1, 0
	s_or_b64 s[42:43], s[2:3], s[42:43]
	s_setprio 1
	v_cndmask_b32_e64 v34, v221, 0, s[6:7]
	s_mul_i32 s6, s78, 0x1400
	v_add_u32_e32 v78, s6, v227
	ds_read_b128 v[66:69], v78 offset:2560
	ds_read_b128 v[70:73], v78
	v_cmp_lt_f32_e32 vcc, s87, v177
	ds_read_b128 v[74:77], v78 offset:32
	s_nop 0
	v_cndmask_b32_e32 v176, 0, v177, vcc
	v_sub_f32_e32 v34, v34, v176
	v_mov_b32_e32 v35, v34
	v_mov_b32_e32 v36, v34
	v_mov_b32_e32 v37, v34
	v_mov_b32_e32 v38, v34
	v_mov_b32_e32 v39, v34
	v_mov_b32_e32 v40, v34
	v_mov_b32_e32 v41, v34
	v_mov_b32_e32 v42, v34
	v_mov_b32_e32 v43, v34
	v_mov_b32_e32 v44, v34
	v_mov_b32_e32 v45, v34
	v_mov_b32_e32 v46, v34
	v_mov_b32_e32 v47, v34
	v_mov_b32_e32 v48, v34
	v_mov_b32_e32 v49, v34
	s_waitcnt lgkmcnt(1)
	s_nop 0
	v_mfma_f32_32x32x16_bf16 v[50:65], v[70:73], v[102:105], v[34:49]
	v_mfma_f32_32x32x16_bf16 v[34:49], v[66:69], v[102:105], v[34:49]
	ds_read_b128 v[66:69], v78 offset:2592
	s_waitcnt lgkmcnt(1)
	v_mfma_f32_32x32x16_bf16 v[50:65], v[74:77], v[98:101], v[50:65]
	s_waitcnt lgkmcnt(0)
	v_mfma_f32_32x32x16_bf16 v[34:49], v[66:69], v[98:101], v[34:49]
	s_setprio 0
	s_andn2_b64 vcc, exec, s[42:43]
	s_mov_b64 s[42:43], -1
	s_cbranch_vccz .LBB0_1263
	s_and_b64 vcc, exec, s[4:5]
	s_cbranch_vccz .LBB0_1259
	v_add3_u32 v66, s90, v224, v0
	ds_read_b128 v[146:149], v66 offset:20480
	ds_read_b128 v[142:145], v66 offset:20512
	ds_read_b128 v[150:153], v66 offset:25088
	ds_read_b128 v[138:141], v66 offset:25120
	ds_read_b128 v[134:137], v66 offset:20544
	ds_read_b128 v[126:129], v66 offset:20576
	ds_read_b128 v[130:133], v66 offset:25152
	ds_read_b128 v[122:125], v66 offset:25184
	v_max_f32_e32 v66, v51, v51
	v_max_f32_e32 v67, v50, v50
	v_max_f32_e32 v66, v67, v66
	v_max3_f32 v66, v66, v52, v53
	v_max3_f32 v66, v66, v54, v55
	v_max3_f32 v66, v66, v56, v57
	v_max3_f32 v66, v66, v58, v59
	v_max3_f32 v66, v66, v60, v61
	v_max3_f32 v66, v66, v62, v63
	v_max3_f32 v66, v66, v64, v65
	v_max3_f32 v66, v66, v34, v35
	v_max3_f32 v66, v66, v36, v37
	v_max3_f32 v66, v66, v38, v39
	v_max3_f32 v66, v66, v40, v41
	v_max3_f32 v66, v66, v42, v43
	v_max3_f32 v66, v66, v44, v45
	v_max3_f32 v66, v66, v46, v47
	v_exp_f32_e32 v204, v50
	v_exp_f32_e32 v180, v34
	v_exp_f32_e32 v205, v51
	v_exp_f32_e32 v181, v35
	v_exp_f32_e32 v206, v52
	v_exp_f32_e32 v188, v36
	v_exp_f32_e32 v207, v53
	v_exp_f32_e32 v189, v37
	v_exp_f32_e32 v208, v54
	v_exp_f32_e32 v194, v38
	v_exp_f32_e32 v209, v55
	v_exp_f32_e32 v195, v39
	v_exp_f32_e32 v192, v56
	v_exp_f32_e32 v196, v40
	v_exp_f32_e32 v193, v57
	v_exp_f32_e32 v197, v41
	v_exp_f32_e32 v198, v58
	v_exp_f32_e32 v178, v42
	v_exp_f32_e32 v199, v59
	v_exp_f32_e32 v179, v43
	v_exp_f32_e32 v202, v60
	v_exp_f32_e32 v182, v44
	v_exp_f32_e32 v203, v61
	v_exp_f32_e32 v183, v45
	v_exp_f32_e32 v200, v62
	v_exp_f32_e32 v190, v46
	v_exp_f32_e32 v201, v63
	v_exp_f32_e32 v191, v47
	v_exp_f32_e32 v184, v64
	v_exp_f32_e32 v186, v48
	v_exp_f32_e32 v185, v65
	v_exp_f32_e32 v187, v49
	v_max3_f32 v156, v66, v48, v49
	v_pk_add_f32 v[66:67], v[176:177], v[156:157]
	v_cmp_neq_f32_e64 s[4:5], v177, v176
	v_cmp_gt_f32_e32 vcc, v66, v67
	s_or_b64 vcc, s[4:5], vcc
	s_cbranch_vccz .LBB0_1257
	v_mov_b32_e32 v66, v210
	v_max_f32_e32 v68, v156, v156
	v_lshlrev_b32_e32 v66, 2, v66
	v_xor_b32_e32 v66, 0x80, v66
	ds_bpermute_b32 v66, v66, v156
	s_waitcnt lgkmcnt(0)
	v_max_f32_e32 v66, v66, v66
	v_max_f32_e32 v66, v68, v66
	v_add_f32_e32 v66, v176, v66
	v_cmp_gt_f32_e32 vcc, v66, v67
	s_nop 1
	v_cndmask_b32_e32 v156, v177, v66, vcc
	v_sub_f32_e32 v66, v176, v156
	v_min_f32_e32 v66, 0x42f00000, v66
	v_sub_f32_e32 v67, v177, v156
	v_exp_f32_e32 v66, v66
	v_exp_f32_e32 v158, v67
	v_pk_mul_f32 v[184:185], v[184:185], v[66:67] op_sel_hi:[1,0]
	v_pk_mul_f32 v[200:201], v[200:201], v[66:67] op_sel_hi:[1,0]
	v_pk_mul_f32 v[202:203], v[202:203], v[66:67] op_sel_hi:[1,0]
	v_pk_mul_f32 v[198:199], v[198:199], v[66:67] op_sel_hi:[1,0]
	v_pk_mul_f32 v[192:193], v[192:193], v[66:67] op_sel_hi:[1,0]
	v_pk_mul_f32 v[208:209], v[208:209], v[66:67] op_sel_hi:[1,0]
	v_pk_mul_f32 v[206:207], v[206:207], v[66:67] op_sel_hi:[1,0]
	v_pk_mul_f32 v[204:205], v[204:205], v[66:67] op_sel_hi:[1,0]
	v_pk_mul_f32 v[186:187], v[186:187], v[66:67] op_sel_hi:[1,0]
	v_pk_mul_f32 v[190:191], v[190:191], v[66:67] op_sel_hi:[1,0]
	v_pk_mul_f32 v[182:183], v[182:183], v[66:67] op_sel_hi:[1,0]
	v_pk_mul_f32 v[178:179], v[178:179], v[66:67] op_sel_hi:[1,0]
	v_pk_mul_f32 v[196:197], v[196:197], v[66:67] op_sel_hi:[1,0]
	v_pk_mul_f32 v[194:195], v[194:195], v[66:67] op_sel_hi:[1,0]
	v_pk_mul_f32 v[188:189], v[188:189], v[66:67] op_sel_hi:[1,0]
	v_pk_mul_f32 v[180:181], v[180:181], v[66:67] op_sel_hi:[1,0]
	v_pk_mul_f32 v[32:33], v[32:33], v[158:159] op_sel_hi:[1,0]
	v_pk_mul_f32 v[30:31], v[30:31], v[158:159] op_sel_hi:[1,0]
	v_pk_mul_f32 v[28:29], v[28:29], v[158:159] op_sel_hi:[1,0]
	v_pk_mul_f32 v[26:27], v[26:27], v[158:159] op_sel_hi:[1,0]
	v_pk_mul_f32 v[24:25], v[24:25], v[158:159] op_sel_hi:[1,0]
	v_pk_mul_f32 v[22:23], v[22:23], v[158:159] op_sel_hi:[1,0]
	v_pk_mul_f32 v[20:21], v[20:21], v[158:159] op_sel_hi:[1,0]
	v_pk_mul_f32 v[18:19], v[18:19], v[158:159] op_sel_hi:[1,0]
	v_pk_mul_f32 v[16:17], v[16:17], v[158:159] op_sel_hi:[1,0]
	v_pk_mul_f32 v[14:15], v[14:15], v[158:159] op_sel_hi:[1,0]
	v_pk_mul_f32 v[12:13], v[12:13], v[158:159] op_sel_hi:[1,0]
	v_pk_mul_f32 v[10:11], v[10:11], v[158:159] op_sel_hi:[1,0]
	v_pk_mul_f32 v[8:9], v[8:9], v[158:159] op_sel_hi:[1,0]
	v_pk_mul_f32 v[6:7], v[6:7], v[158:159] op_sel_hi:[1,0]
	v_pk_mul_f32 v[4:5], v[4:5], v[158:159] op_sel_hi:[1,0]
	v_pk_mul_f32 v[2:3], v[2:3], v[158:159] op_sel_hi:[1,0]
	v_mul_f32_e32 v229, v228, v158
	s_branch .LBB0_1258
; __device__ __forceinline__ unsigned cvt_pk_bf16(float lo, float hi) { const f32x2 v = {lo, hi}; return __builtin_bit_cast(unsigned, __builtin_convertvector(v, bf16v2)); }
; __device__ __forceinline__ void softmax_tile(f32x16& s0, f32x16& s1, SM& st, float boff, ldsp_t vb, int hh, int r) {
;     ...
;   float ls = 0.f;
; #pragma unroll
;   for (int i = 0; i < 16; ++i) ls += s0[i] + s1[i];
;   st.l += ls;
;   bf16x8 pf[2][2];
; #pragma unroll
;   for (int s2 = 0; s2 < 2; ++s2) {
;     u32x4 w0, w1;
;     w0.x = cvt_pk_bf16(s0[8 * s2 + 0], s0[8 * s2 + 1]); w0.y = cvt_pk_bf16(s0[8 * s2 + 2], s0[8 * s2 + 3]); w0.z = cvt_pk_bf16(s0[8 * s2 + 4], s0[8 * s2 + 5]); w0.w = cvt_pk_bf16(s0[8 * s2 + 6], s0[8 * s2 + 7]);
;     w1.x = cvt_pk_bf16(s1[8 * s2 + 0], s1[8 * s2 + 1]); w1.y = cvt_pk_bf16(s1[8 * s2 + 2], s1[8 * s2 + 3]); w1.z = cvt_pk_bf16(s1[8 * s2 + 4], s1[8 * s2 + 5]); w1.w = cvt_pk_bf16(s1[8 * s2 + 6], s1[8 * s2 + 7]);
;     pf[0][s2] = __builtin_bit_cast(bf16x8, w0); pf[1][s2] = __builtin_bit_cast(bf16x8, w1);
;   }
; #pragma unroll
;   for (int kb = 0; kb < 2; ++kb)
; #pragma unroll
;     for (int s2 = 0; s2 < 2; ++s2) {
;       st.o0 = __builtin_amdgcn_mfma_f32_32x32x16_bf16(va0[kb][s2], pf[kb][s2], st.o0, 0, 0, 0);
;       st.o1 = __builtin_amdgcn_mfma_f32_32x32x16_bf16(va1[kb][s2], pf[kb][s2], st.o1, 0, 0, 0);
;     }
; template <int MODE, bool lookup, int MK>
; __device__ __forceinline__ void softmax_pv(f32x16& s0, f32x16& s1, SM& st, float boff, ldsp_t vb, LAS const float* tab, int t, int e_q, int posq, int hh, int r, bool mask_rt, float negv) {
;     ...
;     if (lookup) {
; #pragma unroll
;       for (int i = 0; i < 16; ++i) { const int ek = ekb + (i & 7) + 16 * (i >> 3); int n0 = posq - (ek - koff), n1 = n0 - 32; n0 = (int)min((unsigned)n0, 128u); n1 = (int)min((unsigned)n1, 128u); s0[i] += tab[n0]; s1[i] += tab[n1]; }
;     }
.LBB0_1257:
	v_mov_b32_e32 v156, v177
	v_mov_b32_e32 v229, v228
.LBB0_1258:
	v_cvt_pk_bf16_f32 v158, v204, v205
	v_cvt_pk_bf16_f32 v159, v206, v207
	v_cvt_pk_bf16_f32 v160, v208, v209
	v_cvt_pk_bf16_f32 v161, v192, v193
	s_mov_b64 s[42:43], 0
	s_waitcnt lgkmcnt(7)
	v_mfma_f32_32x32x16_bf16 v[18:33], v[146:149], v[158:161], v[18:33]
	v_cvt_pk_bf16_f32 v146, v198, v199
	v_cvt_pk_bf16_f32 v147, v202, v203
	v_cvt_pk_bf16_f32 v148, v200, v201
	v_cvt_pk_bf16_f32 v149, v184, v185
	s_waitcnt lgkmcnt(5)
	v_mfma_f32_32x32x16_bf16 v[2:17], v[150:153], v[158:161], v[2:17]
	v_add_f32_e32 v150, v204, v180
	v_mfma_f32_32x32x16_bf16 v[18:33], v[142:145], v[146:149], v[18:33]
	v_add_f32_e32 v142, 0, v150
	v_add_f32_e32 v143, v205, v181
	v_add_f32_e32 v142, v143, v142
	v_add_f32_e32 v143, v206, v188
	v_add_f32_e32 v142, v143, v142
	v_add_f32_e32 v143, v207, v189
	v_add_f32_e32 v142, v143, v142
	s_waitcnt lgkmcnt(4)
	v_mfma_f32_32x32x16_bf16 v[2:17], v[138:141], v[146:149], v[2:17]
	v_add_f32_e64 v138, v208, v194
	v_add_f32_e64 v139, v209, v195
	v_cvt_pk_bf16_f32 v140, v194, v195
	v_add_f32_e32 v138, v138, v142
	v_add_f32_e32 v142, v139, v138
	v_cvt_pk_bf16_f32 v138, v180, v181
	v_cvt_pk_bf16_f32 v139, v188, v189
	v_cvt_pk_bf16_f32 v141, v196, v197
	s_waitcnt lgkmcnt(3)
	s_nop 0
	v_mfma_f32_32x32x16_bf16 v[18:33], v[134:137], v[138:141], v[18:33]
	v_add_f32_e64 v134, v192, v196
	v_add_f32_e64 v135, v193, v197
	v_add_f32_e32 v134, v134, v142
	v_add_f32_e32 v136, v135, v134
	v_add_f32_e64 v134, v198, v178
	v_add_f32_e64 v135, v199, v179
	v_add_f32_e32 v134, v134, v136
	s_waitcnt lgkmcnt(1)
	v_mfma_f32_32x32x16_bf16 v[2:17], v[130:133], v[138:141], v[2:17]
	v_add_f32_e32 v136, v135, v134
	v_add_f32_e64 v134, v202, v182
	v_add_f32_e64 v135, v203, v183
	v_cvt_pk_bf16_f32 v131, v182, v183
	v_add_f32_e32 v130, v134, v136
	v_add_f32_e32 v136, v135, v130
	v_pk_add_f32 v[134:135], v[200:201], v[190:191]
	v_cvt_pk_bf16_f32 v130, v178, v179
	v_cvt_pk_bf16_f32 v132, v190, v191
	v_cvt_pk_bf16_f32 v133, v186, v187
	s_nop 1
	v_mfma_f32_32x32x16_bf16 v[18:33], v[126:129], v[130:133], v[18:33]
	v_add_f32_e32 v126, v134, v136
	v_add_f32_e32 v128, v135, v126
	v_add_f32_e64 v126, v184, v186
	v_add_f32_e64 v127, v185, v187
	v_add_f32_e32 v126, v126, v128
	v_add_f32_e32 v126, v127, v126
	v_add_f32_e32 v126, v229, v126
	s_waitcnt lgkmcnt(0)
	v_mfma_f32_32x32x16_bf16 v[2:17], v[122:125], v[130:133], v[2:17]
.LBB0_1259:
	s_and_b64 vcc, exec, s[42:43]
	s_cbranch_vccz .LBB0_1262
	s_nop 0
	v_or_b32_e32 v66, s84, v168
	v_or_b32_e32 v71, 2, v66
	v_or_b32_e32 v73, 3, v66
	v_sub_u32_e32 v67, v225, v66
	v_xad_u32 v69, v66, -1, v225
	v_sub_u32_e32 v71, v225, v71
	v_sub_u32_e32 v73, v225, v73
	v_subrev_u32_e32 v68, 32, v67
	v_subrev_u32_e32 v70, 32, v69
	v_subrev_u32_e32 v72, 32, v71
	v_subrev_u32_e32 v74, 32, v73
	v_or_b32_e32 v75, 4, v66
	v_or_b32_e32 v77, 5, v66
	v_or_b32_e32 v79, 6, v66
	v_or_b32_e32 v81, 7, v66
	v_min_u32_e32 v67, 0x80, v67
	v_min_u32_e32 v68, 0x80, v68
	v_min_u32_e32 v69, 0x80, v69
	v_min_u32_e32 v70, 0x80, v70
	v_min_u32_e32 v71, 0x80, v71
	v_min_u32_e32 v72, 0x80, v72
	v_min_u32_e32 v73, 0x80, v73
	v_min_u32_e32 v74, 0x80, v74
	v_sub_u32_e32 v75, v225, v75
	v_sub_u32_e32 v77, v225, v77
	v_sub_u32_e32 v79, v225, v79
	v_sub_u32_e32 v81, v225, v81
	v_lshl_add_u32 v67, v67, 2, 0
	v_lshl_add_u32 v68, v68, 2, 0
	v_lshl_add_u32 v69, v69, 2, 0
	v_lshl_add_u32 v70, v70, 2, 0
	v_lshl_add_u32 v71, v71, 2, 0
	v_lshl_add_u32 v72, v72, 2, 0
	v_lshl_add_u32 v73, v73, 2, 0
	v_lshl_add_u32 v74, v74, 2, 0
	v_subrev_u32_e32 v76, 32, v75
	v_subrev_u32_e32 v78, 32, v77
	v_subrev_u32_e32 v80, 32, v79
	v_subrev_u32_e32 v82, 32, v81
	v_or_b32_e32 v83, 16, v66
	v_or_b32_e32 v85, 17, v66
	v_or_b32_e32 v87, 18, v66
	v_or_b32_e32 v89, 19, v66
	ds_read_b32 v67, v67 offset:57344
	ds_read_b32 v68, v68 offset:57344
	ds_read_b32 v69, v69 offset:57344
	ds_read_b32 v70, v70 offset:57344
	ds_read_b32 v71, v71 offset:57344
	ds_read_b32 v72, v72 offset:57344
	ds_read_b32 v73, v73 offset:57344
	ds_read_b32 v74, v74 offset:57344
	v_min_u32_e32 v75, 0x80, v75
	v_min_u32_e32 v76, 0x80, v76
	v_min_u32_e32 v77, 0x80, v77
	v_min_u32_e32 v78, 0x80, v78
	v_min_u32_e32 v79, 0x80, v79
	v_min_u32_e32 v80, 0x80, v80
	v_min_u32_e32 v81, 0x80, v81
	v_min_u32_e32 v82, 0x80, v82
	v_sub_u32_e32 v83, v225, v83
	v_sub_u32_e32 v85, v225, v85
	v_sub_u32_e32 v87, v225, v87
	v_sub_u32_e32 v89, v225, v89
	v_lshl_add_u32 v75, v75, 2, 0
	v_lshl_add_u32 v76, v76, 2, 0
	v_lshl_add_u32 v77, v77, 2, 0
	v_lshl_add_u32 v78, v78, 2, 0
	v_lshl_add_u32 v79, v79, 2, 0
	v_lshl_add_u32 v80, v80, 2, 0
	v_lshl_add_u32 v81, v81, 2, 0
	v_lshl_add_u32 v82, v82, 2, 0
	v_subrev_u32_e32 v84, 32, v83
	v_subrev_u32_e32 v86, 32, v85
	v_subrev_u32_e32 v88, 32, v87
	v_subrev_u32_e32 v90, 32, v89
	v_or_b32_e32 v91, 20, v66
	v_or_b32_e32 v93, 21, v66
	v_or_b32_e32 v95, 22, v66
	v_or_b32_e32 v66, 23, v66
	ds_read_b32 v75, v75 offset:57344
	ds_read_b32 v76, v76 offset:57344
	ds_read_b32 v77, v77 offset:57344
	ds_read_b32 v78, v78 offset:57344
	ds_read_b32 v79, v79 offset:57344
	ds_read_b32 v80, v80 offset:57344
	ds_read_b32 v81, v81 offset:57344
	ds_read_b32 v82, v82 offset:57344
	v_min_u32_e32 v83, 0x80, v83
	v_min_u32_e32 v84, 0x80, v84
	v_min_u32_e32 v85, 0x80, v85
	v_min_u32_e32 v86, 0x80, v86
	v_min_u32_e32 v87, 0x80, v87
	v_min_u32_e32 v88, 0x80, v88
	v_min_u32_e32 v89, 0x80, v89
	v_min_u32_e32 v90, 0x80, v90
	v_sub_u32_e32 v91, v225, v91
	v_sub_u32_e32 v93, v225, v93
	v_sub_u32_e32 v95, v225, v95
	v_sub_u32_e32 v66, v225, v66
	s_waitcnt lgkmcnt(14)
	v_add_f32_e32 v67, v50, v67
	s_waitcnt lgkmcnt(13)
; __device__ __forceinline__ float max32(float v) { return __builtin_fmaxf(v, xhalf(v)); }
; __device__ __forceinline__ float max3f(float a, float b, float c) { return __builtin_fmaxf(__builtin_fmaxf(a, b), c); }
; __device__ __forceinline__ void softmax_tile(f32x16& s0, f32x16& s1, SM& st, float boff, ldsp_t vb, int hh, int r) {
;     ...
;   float zmax = max3f(s0[0], s0[1], s0[2]);
; #pragma unroll
;   for (int k = 0; k < 6; ++k) zmax = max3f(zmax, s0[3 + 2 * k], s0[4 + 2 * k]);
;   zmax = max3f(zmax, s0[15], s1[0]);
; #pragma unroll
;   for (int k = 0; k < 7; ++k) zmax = max3f(zmax, s1[1 + 2 * k], s1[2 + 2 * k]);
;   zmax = fmaxf(zmax, s1[15]);
; #pragma unroll
;   for (int i = 0; i < 16; ++i) { s0[i] = __builtin_amdgcn_exp2f(s0[i]); s1[i] = __builtin_amdgcn_exp2f(s1[i]); }
;   if (__any((zmax + boff > st.m + DEFER_THR) || (st.m != boff))) {
;     const float zt = max32(zmax) + boff; const bool need = zt > st.m + DEFER_THR;
;     const float mn = need ? zt : st.m, alpha = __builtin_amdgcn_exp2f(st.m - mn), f = __builtin_amdgcn_exp2f(__builtin_fminf(boff - mn, 120.f)); st.m = mn;
; #pragma unroll
;     for (int i = 0; i < 16; ++i) { s0[i] *= f; s1[i] *= f; st.o0[i] *= alpha; st.o1[i] *= alpha; }
;     st.l *= alpha;
; template <int MODE, bool lookup, int MK>
; __device__ __forceinline__ void softmax_pv(f32x16& s0, f32x16& s1, SM& st, float boff, ldsp_t vb, LAS const float* tab, int t, int e_q, int posq, int hh, int r, bool mask_rt, float negv) {
;     ...
;       for (int i = 0; i < 16; ++i) { const int ek = ekb + (i & 7) + 16 * (i >> 3); int n0 = posq - (ek - koff), n1 = n0 - 32; n0 = (int)min((unsigned)n0, 128u); n1 = (int)min((unsigned)n1, 128u); s0[i] += tab[n0]; s1[i] += tab[n1]; }
	v_add_f32_e32 v69, v51, v69
	v_lshl_add_u32 v83, v83, 2, 0
	v_lshl_add_u32 v84, v84, 2, 0
	v_lshl_add_u32 v85, v85, 2, 0
	v_lshl_add_u32 v86, v86, 2, 0
	v_lshl_add_u32 v87, v87, 2, 0
	v_lshl_add_u32 v88, v88, 2, 0
	v_lshl_add_u32 v89, v89, 2, 0
	v_lshl_add_u32 v90, v90, 2, 0
	v_subrev_u32_e32 v92, 32, v91
	v_subrev_u32_e32 v94, 32, v93
	v_subrev_u32_e32 v96, 32, v95
	v_subrev_u32_e32 v97, 32, v66
	s_waitcnt lgkmcnt(11)
	v_add_f32_e32 v71, v52, v71
	s_waitcnt lgkmcnt(9)
	v_add_f32_e32 v73, v53, v73
	ds_read_b32 v83, v83 offset:57344
	ds_read_b32 v84, v84 offset:57344
	ds_read_b32 v85, v85 offset:57344
	ds_read_b32 v86, v86 offset:57344
	ds_read_b32 v87, v87 offset:57344
	ds_read_b32 v88, v88 offset:57344
	ds_read_b32 v89, v89 offset:57344
	ds_read_b32 v90, v90 offset:57344
	v_min_u32_e32 v91, 0x80, v91
	v_min_u32_e32 v92, 0x80, v92
	v_min_u32_e32 v93, 0x80, v93
	v_min_u32_e32 v94, 0x80, v94
	v_min_u32_e32 v95, 0x80, v95
	v_min_u32_e32 v96, 0x80, v96
	v_min_u32_e32 v66, 0x80, v66
	v_min_u32_e32 v97, 0x80, v97
	v_max_f32_e32 v156, v67, v69
	s_waitcnt lgkmcnt(14)
	v_add_f32_e32 v75, v54, v75
	s_waitcnt lgkmcnt(13)
	v_add_f32_e32 v77, v55, v77
	v_lshl_add_u32 v91, v91, 2, 0
	v_lshl_add_u32 v92, v92, 2, 0
	v_lshl_add_u32 v93, v93, 2, 0
	v_lshl_add_u32 v94, v94, 2, 0
	v_lshl_add_u32 v95, v95, 2, 0
	v_lshl_add_u32 v96, v96, 2, 0
	v_lshl_add_u32 v66, v66, 2, 0
	v_lshl_add_u32 v97, v97, 2, 0
	v_max3_f32 v156, v156, v71, v73
	s_waitcnt lgkmcnt(11)
	v_add_f32_e32 v79, v56, v79
	s_waitcnt lgkmcnt(9)
	v_add_f32_e32 v81, v57, v81
	ds_read_b32 v91, v91 offset:57344
	ds_read_b32 v92, v92 offset:57344
	ds_read_b32 v93, v93 offset:57344
	ds_read_b32 v94, v94 offset:57344
	ds_read_b32 v95, v95 offset:57344
	ds_read_b32 v96, v96 offset:57344
	ds_read_b32 v66, v66 offset:57344
	ds_read_b32 v97, v97 offset:57344
	v_max3_f32 v156, v156, v75, v77
	s_waitcnt lgkmcnt(14)
	v_add_f32_e32 v83, v58, v83
	s_waitcnt lgkmcnt(13)
	v_add_f32_e32 v85, v59, v85
	v_max3_f32 v156, v156, v79, v81
	s_waitcnt lgkmcnt(11)
	v_add_f32_e32 v87, v60, v87
	s_waitcnt lgkmcnt(9)
	v_add_f32_e32 v89, v61, v89
	v_max3_f32 v156, v156, v83, v85
	s_waitcnt lgkmcnt(7)
	v_add_f32_e32 v91, v62, v91
	s_waitcnt lgkmcnt(5)
	v_add_f32_e32 v93, v63, v93
	v_max3_f32 v156, v156, v87, v89
	s_waitcnt lgkmcnt(3)
	v_add_f32_e32 v95, v64, v95
	s_waitcnt lgkmcnt(1)
	v_add_f32_e32 v66, v65, v66
	v_max3_f32 v156, v156, v91, v93
	v_add_f32_e32 v68, v34, v68
	v_add_f32_e32 v70, v35, v70
	v_add3_u32 v122, s90, v224, v0
	v_max3_f32 v156, v156, v95, v66
	v_add_f32_e32 v72, v36, v72
	v_add_f32_e32 v74, v37, v74
	ds_read_b128 v[146:149], v122 offset:20480
	ds_read_b128 v[142:145], v122 offset:20512
	ds_read_b128 v[150:153], v122 offset:25088
	ds_read_b128 v[138:141], v122 offset:25120
	ds_read_b128 v[134:137], v122 offset:20544
	ds_read_b128 v[126:129], v122 offset:20576
	ds_read_b128 v[130:133], v122 offset:25152
	ds_read_b128 v[122:125], v122 offset:25184
	v_max3_f32 v156, v156, v68, v70
	v_add_f32_e32 v76, v38, v76
	v_add_f32_e32 v78, v39, v78
	v_max3_f32 v156, v156, v72, v74
	v_add_f32_e32 v80, v40, v80
	v_add_f32_e32 v82, v41, v82
	v_max3_f32 v156, v156, v76, v78
	v_add_f32_e32 v84, v42, v84
	v_add_f32_e32 v86, v43, v86
	v_max3_f32 v156, v156, v80, v82
	v_add_f32_e32 v88, v44, v88
	v_add_f32_e32 v90, v45, v90
	v_max3_f32 v156, v156, v84, v86
	v_add_f32_e32 v92, v46, v92
	v_add_f32_e32 v94, v47, v94
	v_max3_f32 v156, v156, v88, v90
	v_add_f32_e32 v96, v48, v96
	s_waitcnt lgkmcnt(8)
	v_add_f32_e32 v97, v49, v97
	v_max3_f32 v156, v156, v92, v94
	v_exp_f32_e32 v204, v67
	v_exp_f32_e32 v182, v68
	v_exp_f32_e32 v205, v69
	v_exp_f32_e32 v183, v70
	v_exp_f32_e32 v206, v71
	v_exp_f32_e32 v192, v72
	v_exp_f32_e32 v207, v73
	v_exp_f32_e32 v193, v74
	v_exp_f32_e32 v208, v75
	v_exp_f32_e32 v202, v76
	v_exp_f32_e32 v209, v77
	v_exp_f32_e32 v203, v78
	v_exp_f32_e32 v194, v79
	v_exp_f32_e32 v198, v80
	v_exp_f32_e32 v195, v81
	v_exp_f32_e32 v199, v82
	v_exp_f32_e32 v200, v83
	v_exp_f32_e32 v178, v84
	v_exp_f32_e32 v201, v85
	v_exp_f32_e32 v179, v86
	v_exp_f32_e32 v196, v87
	v_exp_f32_e32 v188, v88
	v_exp_f32_e32 v197, v89
	v_exp_f32_e32 v189, v90
	v_exp_f32_e32 v180, v91
	v_exp_f32_e32 v184, v92
	v_exp_f32_e32 v181, v93
	v_exp_f32_e32 v185, v94
	v_exp_f32_e32 v186, v95
	v_exp_f32_e32 v190, v96
	v_exp_f32_e32 v187, v66
	v_exp_f32_e32 v191, v97
	v_max3_f32 v156, v156, v96, v97
	v_pk_add_f32 v[66:67], v[176:177], v[156:157]
	v_cmp_neq_f32_e64 s[4:5], v177, v176
	v_cmp_gt_f32_e32 vcc, v66, v67
	s_or_b64 vcc, s[4:5], vcc
	s_cbranch_vccz .LBB0_1274
	v_mov_b32_e32 v66, v210
	v_max_f32_e32 v68, v156, v156
	v_lshlrev_b32_e32 v66, 2, v66
	v_xor_b32_e32 v66, 0x80, v66
	ds_bpermute_b32 v66, v66, v156
	s_waitcnt lgkmcnt(0)
	v_max_f32_e32 v66, v66, v66
	v_max_f32_e32 v66, v68, v66
	v_add_f32_e32 v66, v176, v66
	v_cmp_gt_f32_e32 vcc, v66, v67
	s_nop 1
	v_cndmask_b32_e32 v156, v177, v66, vcc
	v_sub_f32_e32 v66, v176, v156
	v_min_f32_e32 v66, 0x42f00000, v66
	v_sub_f32_e32 v67, v177, v156
	v_exp_f32_e32 v66, v66
	v_exp_f32_e32 v158, v67
	v_pk_mul_f32 v[186:187], v[186:187], v[66:67] op_sel_hi:[1,0]
	v_pk_mul_f32 v[180:181], v[180:181], v[66:67] op_sel_hi:[1,0]
	v_pk_mul_f32 v[196:197], v[196:197], v[66:67] op_sel_hi:[1,0]
	v_pk_mul_f32 v[200:201], v[200:201], v[66:67] op_sel_hi:[1,0]
	v_pk_mul_f32 v[194:195], v[194:195], v[66:67] op_sel_hi:[1,0]
	v_pk_mul_f32 v[208:209], v[208:209], v[66:67] op_sel_hi:[1,0]
	v_pk_mul_f32 v[206:207], v[206:207], v[66:67] op_sel_hi:[1,0]
	v_pk_mul_f32 v[204:205], v[204:205], v[66:67] op_sel_hi:[1,0]
	v_pk_mul_f32 v[190:191], v[190:191], v[66:67] op_sel_hi:[1,0]
	v_pk_mul_f32 v[184:185], v[184:185], v[66:67] op_sel_hi:[1,0]
	v_pk_mul_f32 v[188:189], v[188:189], v[66:67] op_sel_hi:[1,0]
	v_pk_mul_f32 v[178:179], v[178:179], v[66:67] op_sel_hi:[1,0]
	v_pk_mul_f32 v[198:199], v[198:199], v[66:67] op_sel_hi:[1,0]
	v_pk_mul_f32 v[202:203], v[202:203], v[66:67] op_sel_hi:[1,0]
	v_pk_mul_f32 v[192:193], v[192:193], v[66:67] op_sel_hi:[1,0]
	v_pk_mul_f32 v[182:183], v[182:183], v[66:67] op_sel_hi:[1,0]
	v_pk_mul_f32 v[32:33], v[32:33], v[158:159] op_sel_hi:[1,0]
	v_pk_mul_f32 v[30:31], v[30:31], v[158:159] op_sel_hi:[1,0]
	v_pk_mul_f32 v[28:29], v[28:29], v[158:159] op_sel_hi:[1,0]
	v_pk_mul_f32 v[26:27], v[26:27], v[158:159] op_sel_hi:[1,0]
	v_pk_mul_f32 v[24:25], v[24:25], v[158:159] op_sel_hi:[1,0]
	v_pk_mul_f32 v[22:23], v[22:23], v[158:159] op_sel_hi:[1,0]
	v_pk_mul_f32 v[20:21], v[20:21], v[158:159] op_sel_hi:[1,0]
	v_pk_mul_f32 v[18:19], v[18:19], v[158:159] op_sel_hi:[1,0]
	v_pk_mul_f32 v[16:17], v[16:17], v[158:159] op_sel_hi:[1,0]
	v_pk_mul_f32 v[14:15], v[14:15], v[158:159] op_sel_hi:[1,0]
	v_pk_mul_f32 v[12:13], v[12:13], v[158:159] op_sel_hi:[1,0]
	v_pk_mul_f32 v[10:11], v[10:11], v[158:159] op_sel_hi:[1,0]
	v_pk_mul_f32 v[8:9], v[8:9], v[158:159] op_sel_hi:[1,0]
	v_pk_mul_f32 v[6:7], v[6:7], v[158:159] op_sel_hi:[1,0]
	v_pk_mul_f32 v[4:5], v[4:5], v[158:159] op_sel_hi:[1,0]
	v_pk_mul_f32 v[2:3], v[2:3], v[158:159] op_sel_hi:[1,0]
	v_mul_f32_e32 v229, v228, v158
	s_branch .LBB0_1275

; #define LAS __attribute__((address_space(3)))
; template <int MODE>
; __device__ __forceinline__ void attn_item(const Params& P, int layer, int b, int h, int map, int qb) {
;     ...
;   auto issue = [&](Stage& st, int t) {
; #pragma unroll
;     for (int u = 0; u < NLK; ++u) { int c = tid + 512 * u; if (c >= NKC) c -= (NKC % 512 == 0 ? 512 : NKC % 512);
;       const int row = c / CPR, cc = c % CPR; st.k[u] = *(const u32x4*)(kp + (size_t)(64 * t + row) * KLD + cc * 8); }
;     { const int row = tid >> 3, cc = tid & 7; st.v = *(const u32x4*)(vp + (size_t)row * E + 64 * t + cc * 8); }
;   };
;   auto commit = [&](const Stage& st, int bufi) {
; #pragma unroll
;     for (int u = 0; u < NLK; ++u) { int c = tid + 512 * u; if (c >= NKC) c -= (NKC % 512 == 0 ? 512 : NKC % 512);
;       const int row = c / CPR, cc = c % CPR; *(LAS u32x4*)(lds + bufi * KBUF + row * KSTR + cc * 16) = st.k[u]; }
;     { const int row = tid >> 3, cc = tid & 7; *(LAS u32x4*)(lds + 4 * KBUF + bufi * VBUF + row * 144 + cc * 16) = st.v; }
;   };
;   auto tile_of = [&](int i) { return i == 0 ? 0 : tstart + i - 1; };
;   auto skipf = [&](int t) { bool sk = !active; if (t > 0) { if (64 * t > eq0 + 31) sk = true; if (MODE == 2 && eq0 - (64 * t + 63) >= 128) sk = true; } return sk; };
;   const int pr = (r & 0x13) | ((r & 4) << 1) | ((r & 8) >> 1);
;   auto lookf = [&](int t) { return MODE != 0 && (t == 0 || MODE == 2 || (eq0 - (64 * t + 63) < 128)); };
;   auto qk = [&](f32x16& s0, f32x16& s1, float& boff, int bufi, int t) {
;     const ldsp_t kbuf = lds + bufi * KBUF;
;     __builtin_amdgcn_s_setprio(1);
;     boff = sa.m > -1e29f ? sa.m : 0.f;
;     const float init = ((MODE == 1 && !lookf(t)) ? cfar : 0.f) - boff;
; #pragma unroll
;     for (int q = 0; q < 16; ++q) { s0[q] = init; s1[q] = init; }
; #pragma unroll
;     for (int s = 0; s < NST; ++s) {
;       const bf16x8 a0 = *(LAS const bf16x8*)(kbuf + pr * KSTR + s * 32 + hh * 16);
;       const bf16x8 a1 = *(LAS const bf16x8*)(kbuf + (32 + pr) * KSTR + s * 32 + hh * 16);
;       s0 = __builtin_amdgcn_mfma_f32_32x32x16_bf16(a0, qf[s], s0, 0, 0, 0);
;       s1 = __builtin_amdgcn_mfma_f32_32x32x16_bf16(a1, qf[s], s1, 0, 0, 0);
;     }
;     __builtin_amdgcn_sched_group_barrier(0x100, 4, 0);
; #pragma unroll
;     for (int s = 0; s < NST - 2; ++s) { __builtin_amdgcn_sched_group_barrier(0x8, 2, 0); __builtin_amdgcn_sched_group_barrier(0x100, 2, 0); }
.LBB0_1268:
	s_xor_b32 s2, s78, 2
	s_mul_i32 s3, s2, 0x1400
	v_add_u32_e32 v34, s3, v171
	s_mulk_i32 s2, 0x2400
	s_waitcnt vmcnt(3)
	ds_write_b128 v34, v[106:109]
	v_add_u32_e32 v34, s2, v222
	s_add_i32 s2, s48, 4
	s_min_i32 s2, s2, s63
	s_lshl_b32 s90, s2, 6
	s_waitcnt vmcnt(2)
	ds_write_b128 v34, v[110:113] offset:20480
	v_add_u32_e32 v34, s90, v170
	v_ashrrev_i32_e32 v35, 31, v34
	v_lshlrev_b64 v[34:35], 7, v[34:35]
	v_lshl_add_u64 v[34:35], v[174:175], 0, v[34:35]
	v_lshl_add_u64 v[36:37], s[90:91], 1, v[172:173]
	global_load_dwordx4 v[106:109], v[34:35], off
	global_load_dwordx4 v[110:113], v[36:37], off
	s_or_b32 s2, s48, 1
	s_cmp_ge_u32 s2, s62
	s_cbranch_scc1 .LBB0_1250
	s_lshl_b32 s5, s2, 6
	s_cmp_le_i32 s5, s37
	s_cselect_b64 s[2:3], -1, 0
	s_and_b64 s[2:3], s[2:3], s[68:69]
	s_andn2_b64 vcc, exec, s[2:3]
	s_cbranch_vccnz .LBB0_1250
	s_sub_i32 s2, s80, s5
	s_cmpk_gt_i32 s2, 0x7f
	s_cselect_b64 vcc, -1, 0
	s_or_b32 s6, s78, 1
	s_mul_i32 s2, s6, 0x2400
	s_add_i32 s4, s2, 0
	s_or_b32 s2, s5, 63
	s_cmp_le_i32 s2, s36
	s_setprio 1
	s_mulk_i32 s6, 0x1400
	v_add_u32_e32 v78, s6, v227
	ds_read_b128 v[66:69], v78 offset:2560
	ds_read_b128 v[70:73], v78
	v_cmp_lt_f32_e64 s[2:3], s87, v177
	v_cndmask_b32_e32 v34, 0, v221, vcc
	ds_read_b128 v[74:77], v78 offset:32
	v_cndmask_b32_e64 v176, 0, v177, s[2:3]
	v_sub_f32_e32 v34, v34, v176
	v_mov_b32_e32 v35, v34
	v_mov_b32_e32 v36, v34
	v_mov_b32_e32 v37, v34
	v_mov_b32_e32 v38, v34
	v_mov_b32_e32 v39, v34
	v_mov_b32_e32 v40, v34
	v_mov_b32_e32 v41, v34
	v_mov_b32_e32 v42, v34
	v_mov_b32_e32 v43, v34
	v_mov_b32_e32 v44, v34
	v_mov_b32_e32 v45, v34
	v_mov_b32_e32 v46, v34
	v_mov_b32_e32 v47, v34
	v_mov_b32_e32 v48, v34
	v_mov_b32_e32 v49, v34
	s_waitcnt lgkmcnt(1)
	s_nop 0
	v_mfma_f32_32x32x16_bf16 v[50:65], v[70:73], v[102:105], v[34:49]
	v_mfma_f32_32x32x16_bf16 v[34:49], v[66:69], v[102:105], v[34:49]
	ds_read_b128 v[66:69], v78 offset:2592
	s_waitcnt lgkmcnt(1)
	v_mfma_f32_32x32x16_bf16 v[50:65], v[74:77], v[98:101], v[50:65]
	s_waitcnt lgkmcnt(0)
	v_mfma_f32_32x32x16_bf16 v[34:49], v[66:69], v[98:101], v[34:49]
	s_setprio 0
	s_mov_b64 s[2:3], -1
	s_cbranch_scc0 .LBB0_1282
	s_and_b64 vcc, exec, vcc
	s_cbranch_vccz .LBB0_1278
	v_add3_u32 v66, s4, v224, v0
	ds_read_b128 v[146:149], v66 offset:20480
	ds_read_b128 v[142:145], v66 offset:20512
	ds_read_b128 v[150:153], v66 offset:25088
	ds_read_b128 v[138:141], v66 offset:25120
	ds_read_b128 v[134:137], v66 offset:20544
	ds_read_b128 v[126:129], v66 offset:20576
	ds_read_b128 v[130:133], v66 offset:25152
	ds_read_b128 v[122:125], v66 offset:25184
	v_max_f32_e32 v66, v51, v51
	v_max_f32_e32 v67, v50, v50
	v_max_f32_e32 v66, v67, v66
	v_max3_f32 v66, v66, v52, v53
	v_max3_f32 v66, v66, v54, v55
	v_max3_f32 v66, v66, v56, v57
	v_max3_f32 v66, v66, v58, v59
	v_max3_f32 v66, v66, v60, v61
	v_max3_f32 v66, v66, v62, v63
	v_max3_f32 v66, v66, v64, v65
	v_max3_f32 v66, v66, v34, v35
	v_max3_f32 v66, v66, v36, v37
	v_max3_f32 v66, v66, v38, v39
	v_max3_f32 v66, v66, v40, v41
	v_max3_f32 v66, v66, v42, v43
	v_max3_f32 v66, v66, v44, v45
	v_max3_f32 v66, v66, v46, v47
	v_exp_f32_e32 v204, v50
	v_exp_f32_e32 v180, v34
	v_exp_f32_e32 v205, v51
	v_exp_f32_e32 v181, v35
	v_exp_f32_e32 v206, v52
	v_exp_f32_e32 v188, v36
	v_exp_f32_e32 v207, v53
	v_exp_f32_e32 v189, v37
	v_exp_f32_e32 v208, v54
	v_exp_f32_e32 v194, v38
	v_exp_f32_e32 v209, v55
	v_exp_f32_e32 v195, v39
	v_exp_f32_e32 v192, v56
	v_exp_f32_e32 v196, v40
	v_exp_f32_e32 v193, v57
	v_exp_f32_e32 v197, v41
	v_exp_f32_e32 v198, v58
	v_exp_f32_e32 v178, v42
	v_exp_f32_e32 v199, v59
	v_exp_f32_e32 v179, v43
	v_exp_f32_e32 v202, v60
	v_exp_f32_e32 v182, v44
	v_exp_f32_e32 v203, v61
	v_exp_f32_e32 v183, v45
	v_exp_f32_e32 v200, v62
	v_exp_f32_e32 v190, v46
	v_exp_f32_e32 v201, v63
	v_exp_f32_e32 v191, v47
	v_exp_f32_e32 v184, v64
	v_exp_f32_e32 v186, v48
	v_exp_f32_e32 v185, v65
	v_exp_f32_e32 v187, v49
	v_max3_f32 v156, v66, v48, v49
	v_pk_add_f32 v[66:67], v[176:177], v[156:157]
	v_cmp_neq_f32_e64 s[2:3], v177, v176
	v_cmp_gt_f32_e32 vcc, v66, v67
	s_or_b64 vcc, s[2:3], vcc
	s_cbranch_vccz .LBB0_1276
	v_mov_b32_e32 v66, v210
	v_max_f32_e32 v68, v156, v156
	v_lshlrev_b32_e32 v66, 2, v66
	v_xor_b32_e32 v66, 0x80, v66
	ds_bpermute_b32 v66, v66, v156
	s_waitcnt lgkmcnt(0)
	v_max_f32_e32 v66, v66, v66
	v_max_f32_e32 v66, v68, v66
	v_add_f32_e32 v66, v176, v66
	v_cmp_gt_f32_e32 vcc, v66, v67
	s_nop 1
	v_cndmask_b32_e32 v156, v177, v66, vcc
	v_sub_f32_e32 v66, v176, v156
	v_min_f32_e32 v66, 0x42f00000, v66
	v_sub_f32_e32 v67, v177, v156
	v_exp_f32_e32 v66, v66
	v_exp_f32_e32 v158, v67
	v_pk_mul_f32 v[184:185], v[184:185], v[66:67] op_sel_hi:[1,0]
	v_pk_mul_f32 v[200:201], v[200:201], v[66:67] op_sel_hi:[1,0]
	v_pk_mul_f32 v[202:203], v[202:203], v[66:67] op_sel_hi:[1,0]
	v_pk_mul_f32 v[198:199], v[198:199], v[66:67] op_sel_hi:[1,0]
	v_pk_mul_f32 v[192:193], v[192:193], v[66:67] op_sel_hi:[1,0]
	v_pk_mul_f32 v[208:209], v[208:209], v[66:67] op_sel_hi:[1,0]
	v_pk_mul_f32 v[206:207], v[206:207], v[66:67] op_sel_hi:[1,0]
	v_pk_mul_f32 v[204:205], v[204:205], v[66:67] op_sel_hi:[1,0]
	v_pk_mul_f32 v[186:187], v[186:187], v[66:67] op_sel_hi:[1,0]
	v_pk_mul_f32 v[190:191], v[190:191], v[66:67] op_sel_hi:[1,0]
	v_pk_mul_f32 v[182:183], v[182:183], v[66:67] op_sel_hi:[1,0]
	v_pk_mul_f32 v[178:179], v[178:179], v[66:67] op_sel_hi:[1,0]
	v_pk_mul_f32 v[196:197], v[196:197], v[66:67] op_sel_hi:[1,0]
	v_pk_mul_f32 v[194:195], v[194:195], v[66:67] op_sel_hi:[1,0]
	v_pk_mul_f32 v[188:189], v[188:189], v[66:67] op_sel_hi:[1,0]
	v_pk_mul_f32 v[180:181], v[180:181], v[66:67] op_sel_hi:[1,0]
	v_pk_mul_f32 v[32:33], v[32:33], v[158:159] op_sel_hi:[1,0]
	v_pk_mul_f32 v[30:31], v[30:31], v[158:159] op_sel_hi:[1,0]
	v_pk_mul_f32 v[28:29], v[28:29], v[158:159] op_sel_hi:[1,0]
	v_pk_mul_f32 v[26:27], v[26:27], v[158:159] op_sel_hi:[1,0]
	v_pk_mul_f32 v[24:25], v[24:25], v[158:159] op_sel_hi:[1,0]
	v_pk_mul_f32 v[22:23], v[22:23], v[158:159] op_sel_hi:[1,0]
	v_pk_mul_f32 v[20:21], v[20:21], v[158:159] op_sel_hi:[1,0]
	v_pk_mul_f32 v[18:19], v[18:19], v[158:159] op_sel_hi:[1,0]
	v_pk_mul_f32 v[16:17], v[16:17], v[158:159] op_sel_hi:[1,0]
	v_pk_mul_f32 v[14:15], v[14:15], v[158:159] op_sel_hi:[1,0]
	v_pk_mul_f32 v[12:13], v[12:13], v[158:159] op_sel_hi:[1,0]
	v_pk_mul_f32 v[10:11], v[10:11], v[158:159] op_sel_hi:[1,0]
	v_pk_mul_f32 v[8:9], v[8:9], v[158:159] op_sel_hi:[1,0]
	v_pk_mul_f32 v[6:7], v[6:7], v[158:159] op_sel_hi:[1,0]
	v_pk_mul_f32 v[4:5], v[4:5], v[158:159] op_sel_hi:[1,0]
	v_pk_mul_f32 v[2:3], v[2:3], v[158:159] op_sel_hi:[1,0]
	v_mul_f32_e32 v229, v228, v158
	s_branch .LBB0_1277

; __device__ __forceinline__ unsigned cvt_pk_bf16(float lo, float hi) { const f32x2 v = {lo, hi}; return __builtin_bit_cast(unsigned, __builtin_convertvector(v, bf16v2)); }
; __device__ __forceinline__ void softmax_tile(f32x16& s0, f32x16& s1, SM& st, float boff, ldsp_t vb, int hh, int r) {
;     ...
;   float ls = 0.f;
; #pragma unroll
;   for (int i = 0; i < 16; ++i) ls += s0[i] + s1[i];
;   st.l += ls;
;   bf16x8 pf[2][2];
; #pragma unroll
;   for (int s2 = 0; s2 < 2; ++s2) {
;     u32x4 w0, w1;
;     w0.x = cvt_pk_bf16(s0[8 * s2 + 0], s0[8 * s2 + 1]); w0.y = cvt_pk_bf16(s0[8 * s2 + 2], s0[8 * s2 + 3]); w0.z = cvt_pk_bf16(s0[8 * s2 + 4], s0[8 * s2 + 5]); w0.w = cvt_pk_bf16(s0[8 * s2 + 6], s0[8 * s2 + 7]);
;     w1.x = cvt_pk_bf16(s1[8 * s2 + 0], s1[8 * s2 + 1]); w1.y = cvt_pk_bf16(s1[8 * s2 + 2], s1[8 * s2 + 3]); w1.z = cvt_pk_bf16(s1[8 * s2 + 4], s1[8 * s2 + 5]); w1.w = cvt_pk_bf16(s1[8 * s2 + 6], s1[8 * s2 + 7]);
;     pf[0][s2] = __builtin_bit_cast(bf16x8, w0); pf[1][s2] = __builtin_bit_cast(bf16x8, w1);
;   }
; #pragma unroll
;   for (int kb = 0; kb < 2; ++kb)
; #pragma unroll
;     for (int s2 = 0; s2 < 2; ++s2) {
;       st.o0 = __builtin_amdgcn_mfma_f32_32x32x16_bf16(va0[kb][s2], pf[kb][s2], st.o0, 0, 0, 0);
;       st.o1 = __builtin_amdgcn_mfma_f32_32x32x16_bf16(va1[kb][s2], pf[kb][s2], st.o1, 0, 0, 0);
;     }
.LBB0_1275:
	v_cvt_pk_bf16_f32 v158, v204, v205
	v_cvt_pk_bf16_f32 v159, v206, v207
	v_cvt_pk_bf16_f32 v160, v208, v209
	v_cvt_pk_bf16_f32 v161, v194, v195
	s_waitcnt lgkmcnt(7)
	s_nop 0
	v_mfma_f32_32x32x16_bf16 v[18:33], v[146:149], v[158:161], v[18:33]
	v_cvt_pk_bf16_f32 v146, v200, v201
	v_cvt_pk_bf16_f32 v147, v196, v197
	v_cvt_pk_bf16_f32 v148, v180, v181
	v_cvt_pk_bf16_f32 v149, v186, v187
	s_waitcnt lgkmcnt(5)
	v_mfma_f32_32x32x16_bf16 v[2:17], v[150:153], v[158:161], v[2:17]
	v_mfma_f32_32x32x16_bf16 v[18:33], v[142:145], v[146:149], v[18:33]
	v_add_f32_e32 v142, v204, v182
	v_add_f32_e32 v142, 0, v142
	v_add_f32_e32 v143, v205, v183
	v_add_f32_e32 v142, v143, v142
	v_add_f32_e32 v143, v206, v192
	v_add_f32_e32 v142, v143, v142
	v_add_f32_e32 v143, v207, v193
	s_waitcnt lgkmcnt(4)
	v_mfma_f32_32x32x16_bf16 v[2:17], v[138:141], v[146:149], v[2:17]
	v_add_f32_e32 v138, v143, v142
	v_add_f32_e64 v142, v208, v202
	v_add_f32_e64 v143, v209, v203
	v_cvt_pk_bf16_f32 v139, v192, v193
	v_add_f32_e32 v142, v142, v138
	v_cvt_pk_bf16_f32 v138, v182, v183
	v_cvt_pk_bf16_f32 v140, v202, v203
	v_cvt_pk_bf16_f32 v141, v198, v199
	s_waitcnt lgkmcnt(3)
	s_nop 0
	v_mfma_f32_32x32x16_bf16 v[18:33], v[134:137], v[138:141], v[18:33]
	v_add_f32_e32 v136, v143, v142
	v_add_f32_e64 v134, v194, v198
	v_add_f32_e64 v135, v195, v199
	v_add_f32_e32 v134, v134, v136
	v_add_f32_e32 v136, v135, v134
	v_pk_add_f32 v[134:135], v[200:201], v[178:179]
	s_nop 0
	v_add_f32_e32 v134, v134, v136
	v_add_f32_e32 v134, v135, v134
	s_waitcnt lgkmcnt(1)
	v_mfma_f32_32x32x16_bf16 v[2:17], v[130:133], v[138:141], v[2:17]
	v_add_f32_e64 v130, v196, v188
	v_add_f32_e64 v131, v197, v189
	v_cvt_pk_bf16_f32 v132, v184, v185
	v_add_f32_e32 v130, v130, v134
	v_add_f32_e32 v134, v131, v130
	v_cvt_pk_bf16_f32 v130, v178, v179
	v_cvt_pk_bf16_f32 v131, v188, v189
	v_cvt_pk_bf16_f32 v133, v190, v191
	s_nop 1
	v_mfma_f32_32x32x16_bf16 v[18:33], v[126:129], v[130:133], v[18:33]
	v_add_f32_e64 v126, v180, v184
	v_add_f32_e64 v127, v181, v185
	v_add_f32_e32 v126, v126, v134
	v_add_f32_e32 v128, v127, v126
	v_add_f32_e64 v126, v186, v190
	v_add_f32_e64 v127, v187, v191
	v_add_f32_e32 v126, v126, v128
	v_add_f32_e32 v126, v127, v126
	v_add_f32_e32 v126, v229, v126
	s_waitcnt lgkmcnt(0)
	v_mfma_f32_32x32x16_bf16 v[2:17], v[122:125], v[130:133], v[2:17]
	s_cbranch_execz .LBB0_1264
	s_branch .LBB0_1267

; __device__ __forceinline__ unsigned cvt_pk_bf16(float lo, float hi) { const f32x2 v = {lo, hi}; return __builtin_bit_cast(unsigned, __builtin_convertvector(v, bf16v2)); }
; __device__ __forceinline__ void softmax_tile(f32x16& s0, f32x16& s1, SM& st, float boff, ldsp_t vb, int hh, int r) {
;     ...
;   float ls = 0.f;
; #pragma unroll
;   for (int i = 0; i < 16; ++i) ls += s0[i] + s1[i];
;   st.l += ls;
;   bf16x8 pf[2][2];
; #pragma unroll
;   for (int s2 = 0; s2 < 2; ++s2) {
;     u32x4 w0, w1;
;     w0.x = cvt_pk_bf16(s0[8 * s2 + 0], s0[8 * s2 + 1]); w0.y = cvt_pk_bf16(s0[8 * s2 + 2], s0[8 * s2 + 3]); w0.z = cvt_pk_bf16(s0[8 * s2 + 4], s0[8 * s2 + 5]); w0.w = cvt_pk_bf16(s0[8 * s2 + 6], s0[8 * s2 + 7]);
;     w1.x = cvt_pk_bf16(s1[8 * s2 + 0], s1[8 * s2 + 1]); w1.y = cvt_pk_bf16(s1[8 * s2 + 2], s1[8 * s2 + 3]); w1.z = cvt_pk_bf16(s1[8 * s2 + 4], s1[8 * s2 + 5]); w1.w = cvt_pk_bf16(s1[8 * s2 + 6], s1[8 * s2 + 7]);
;     pf[0][s2] = __builtin_bit_cast(bf16x8, w0); pf[1][s2] = __builtin_bit_cast(bf16x8, w1);
;   }
; #pragma unroll
;   for (int kb = 0; kb < 2; ++kb)
; #pragma unroll
;     for (int s2 = 0; s2 < 2; ++s2) {
;       st.o0 = __builtin_amdgcn_mfma_f32_32x32x16_bf16(va0[kb][s2], pf[kb][s2], st.o0, 0, 0, 0);
;       st.o1 = __builtin_amdgcn_mfma_f32_32x32x16_bf16(va1[kb][s2], pf[kb][s2], st.o1, 0, 0, 0);
;     }
; template <int MODE, bool lookup, int MK>
; __device__ __forceinline__ void softmax_pv(f32x16& s0, f32x16& s1, SM& st, float boff, ldsp_t vb, LAS const float* tab, int t, int e_q, int posq, int hh, int r, bool mask_rt, float negv) {
;     ...
;       for (int i = 0; i < 16; ++i) { const int ek = ekb + (i & 7) + 16 * (i >> 3); int n0 = posq - (ek - koff), n1 = n0 - 32; n0 = (int)min((unsigned)n0, 128u); n1 = (int)min((unsigned)n1, 128u); s0[i] += tab[n0]; s1[i] += tab[n1]; }
.LBB0_1277:
	v_cvt_pk_bf16_f32 v158, v204, v205
	v_cvt_pk_bf16_f32 v159, v206, v207
	v_cvt_pk_bf16_f32 v160, v208, v209
	v_cvt_pk_bf16_f32 v161, v192, v193
	s_mov_b64 s[2:3], 0
	s_waitcnt lgkmcnt(7)
	v_mfma_f32_32x32x16_bf16 v[18:33], v[146:149], v[158:161], v[18:33]
	v_cvt_pk_bf16_f32 v146, v198, v199
	v_cvt_pk_bf16_f32 v147, v202, v203
	v_cvt_pk_bf16_f32 v148, v200, v201
	v_cvt_pk_bf16_f32 v149, v184, v185
	s_waitcnt lgkmcnt(5)
	v_mfma_f32_32x32x16_bf16 v[2:17], v[150:153], v[158:161], v[2:17]
	v_add_f32_e32 v150, v204, v180
	v_mfma_f32_32x32x16_bf16 v[18:33], v[142:145], v[146:149], v[18:33]
	v_add_f32_e32 v142, 0, v150
	v_add_f32_e32 v143, v205, v181
	v_add_f32_e32 v142, v143, v142
	v_add_f32_e32 v143, v206, v188
	v_add_f32_e32 v142, v143, v142
	v_add_f32_e32 v143, v207, v189
	v_add_f32_e32 v142, v143, v142
	s_waitcnt lgkmcnt(4)
	v_mfma_f32_32x32x16_bf16 v[2:17], v[138:141], v[146:149], v[2:17]
	v_add_f32_e64 v138, v208, v194
	v_add_f32_e64 v139, v209, v195
	v_cvt_pk_bf16_f32 v140, v194, v195
	v_add_f32_e32 v138, v138, v142
	v_add_f32_e32 v142, v139, v138
	v_cvt_pk_bf16_f32 v138, v180, v181
	v_cvt_pk_bf16_f32 v139, v188, v189
	v_cvt_pk_bf16_f32 v141, v196, v197
	s_waitcnt lgkmcnt(3)
	s_nop 0
	v_mfma_f32_32x32x16_bf16 v[18:33], v[134:137], v[138:141], v[18:33]
	v_add_f32_e64 v134, v192, v196
	v_add_f32_e64 v135, v193, v197
	v_add_f32_e32 v134, v134, v142
	v_add_f32_e32 v136, v135, v134
	v_add_f32_e64 v134, v198, v178
	v_add_f32_e64 v135, v199, v179
	v_add_f32_e32 v134, v134, v136
	s_waitcnt lgkmcnt(1)
	v_mfma_f32_32x32x16_bf16 v[2:17], v[130:133], v[138:141], v[2:17]
	v_add_f32_e32 v136, v135, v134
	v_add_f32_e64 v134, v202, v182
	v_add_f32_e64 v135, v203, v183
	v_cvt_pk_bf16_f32 v131, v182, v183
	v_add_f32_e32 v130, v134, v136
	v_add_f32_e32 v136, v135, v130
	v_pk_add_f32 v[134:135], v[200:201], v[190:191]
	v_cvt_pk_bf16_f32 v130, v178, v179
	v_cvt_pk_bf16_f32 v132, v190, v191
	v_cvt_pk_bf16_f32 v133, v186, v187
	s_nop 1
	v_mfma_f32_32x32x16_bf16 v[18:33], v[126:129], v[130:133], v[18:33]
	v_add_f32_e32 v126, v134, v136
	v_add_f32_e32 v128, v135, v126
	v_add_f32_e64 v126, v184, v186
	v_add_f32_e64 v127, v185, v187
	v_add_f32_e32 v126, v126, v128
	v_add_f32_e32 v126, v127, v126
	v_add_f32_e32 v126, v229, v126
	s_waitcnt lgkmcnt(0)
	v_mfma_f32_32x32x16_bf16 v[2:17], v[122:125], v[130:133], v[2:17]
.LBB0_1278:
	s_and_b64 vcc, exec, s[2:3]
	s_cbranch_vccz .LBB0_1281
	s_nop 0
	v_or_b32_e32 v66, s5, v168
	v_or_b32_e32 v71, 2, v66
	v_or_b32_e32 v73, 3, v66
	v_sub_u32_e32 v67, v225, v66
	v_xad_u32 v69, v66, -1, v225
	v_sub_u32_e32 v71, v225, v71
	v_sub_u32_e32 v73, v225, v73
	v_subrev_u32_e32 v68, 32, v67
	v_subrev_u32_e32 v70, 32, v69
	v_subrev_u32_e32 v72, 32, v71
	v_subrev_u32_e32 v74, 32, v73
	v_or_b32_e32 v75, 4, v66
	v_or_b32_e32 v77, 5, v66
	v_or_b32_e32 v79, 6, v66
	v_or_b32_e32 v81, 7, v66
	v_min_u32_e32 v67, 0x80, v67
	v_min_u32_e32 v68, 0x80, v68
	v_min_u32_e32 v69, 0x80, v69
	v_min_u32_e32 v70, 0x80, v70
	v_min_u32_e32 v71, 0x80, v71
	v_min_u32_e32 v72, 0x80, v72
	v_min_u32_e32 v73, 0x80, v73
	v_min_u32_e32 v74, 0x80, v74
	v_sub_u32_e32 v75, v225, v75
	v_sub_u32_e32 v77, v225, v77
	v_sub_u32_e32 v79, v225, v79
	v_sub_u32_e32 v81, v225, v81
	v_lshl_add_u32 v67, v67, 2, 0
	v_lshl_add_u32 v68, v68, 2, 0
	v_lshl_add_u32 v69, v69, 2, 0
	v_lshl_add_u32 v70, v70, 2, 0
	v_lshl_add_u32 v71, v71, 2, 0
	v_lshl_add_u32 v72, v72, 2, 0
	v_lshl_add_u32 v73, v73, 2, 0
	v_lshl_add_u32 v74, v74, 2, 0
	v_subrev_u32_e32 v76, 32, v75
	v_subrev_u32_e32 v78, 32, v77
	v_subrev_u32_e32 v80, 32, v79
	v_subrev_u32_e32 v82, 32, v81
	v_or_b32_e32 v83, 16, v66
	v_or_b32_e32 v85, 17, v66
	v_or_b32_e32 v87, 18, v66
	v_or_b32_e32 v89, 19, v66
	ds_read_b32 v67, v67 offset:57344
	ds_read_b32 v68, v68 offset:57344
	ds_read_b32 v69, v69 offset:57344
	ds_read_b32 v70, v70 offset:57344
	ds_read_b32 v71, v71 offset:57344
	ds_read_b32 v72, v72 offset:57344
	ds_read_b32 v73, v73 offset:57344
	ds_read_b32 v74, v74 offset:57344
	v_min_u32_e32 v75, 0x80, v75
	v_min_u32_e32 v76, 0x80, v76
	v_min_u32_e32 v77, 0x80, v77
	v_min_u32_e32 v78, 0x80, v78
	v_min_u32_e32 v79, 0x80, v79
	v_min_u32_e32 v80, 0x80, v80
	v_min_u32_e32 v81, 0x80, v81
	v_min_u32_e32 v82, 0x80, v82
	v_sub_u32_e32 v83, v225, v83
	v_sub_u32_e32 v85, v225, v85
	v_sub_u32_e32 v87, v225, v87
	v_sub_u32_e32 v89, v225, v89
	v_lshl_add_u32 v75, v75, 2, 0
	v_lshl_add_u32 v76, v76, 2, 0
	v_lshl_add_u32 v77, v77, 2, 0
	v_lshl_add_u32 v78, v78, 2, 0
	v_lshl_add_u32 v79, v79, 2, 0
	v_lshl_add_u32 v80, v80, 2, 0
	v_lshl_add_u32 v81, v81, 2, 0
	v_lshl_add_u32 v82, v82, 2, 0
	v_subrev_u32_e32 v84, 32, v83
	v_subrev_u32_e32 v86, 32, v85
	v_subrev_u32_e32 v88, 32, v87
	v_subrev_u32_e32 v90, 32, v89
	v_or_b32_e32 v91, 20, v66
	v_or_b32_e32 v93, 21, v66
	v_or_b32_e32 v95, 22, v66
	v_or_b32_e32 v66, 23, v66
	ds_read_b32 v75, v75 offset:57344
	ds_read_b32 v76, v76 offset:57344
	ds_read_b32 v77, v77 offset:57344
	ds_read_b32 v78, v78 offset:57344
	ds_read_b32 v79, v79 offset:57344
	ds_read_b32 v80, v80 offset:57344
	ds_read_b32 v81, v81 offset:57344
	ds_read_b32 v82, v82 offset:57344
	v_min_u32_e32 v83, 0x80, v83
	v_min_u32_e32 v84, 0x80, v84
	v_min_u32_e32 v85, 0x80, v85
	v_min_u32_e32 v86, 0x80, v86
	v_min_u32_e32 v87, 0x80, v87
	v_min_u32_e32 v88, 0x80, v88
	v_min_u32_e32 v89, 0x80, v89
	v_min_u32_e32 v90, 0x80, v90
	v_sub_u32_e32 v91, v225, v91
	v_sub_u32_e32 v93, v225, v93
	v_sub_u32_e32 v95, v225, v95
	v_sub_u32_e32 v66, v225, v66
	s_waitcnt lgkmcnt(14)
	v_add_f32_e32 v67, v50, v67
	s_waitcnt lgkmcnt(13)
; __device__ __forceinline__ float max32(float v) { return __builtin_fmaxf(v, xhalf(v)); }
; __device__ __forceinline__ float max3f(float a, float b, float c) { return __builtin_fmaxf(__builtin_fmaxf(a, b), c); }
; __device__ __forceinline__ void softmax_tile(f32x16& s0, f32x16& s1, SM& st, float boff, ldsp_t vb, int hh, int r) {
;     ...
;   float zmax = max3f(s0[0], s0[1], s0[2]);
; #pragma unroll
;   for (int k = 0; k < 6; ++k) zmax = max3f(zmax, s0[3 + 2 * k], s0[4 + 2 * k]);
;   zmax = max3f(zmax, s0[15], s1[0]);
; #pragma unroll
;   for (int k = 0; k < 7; ++k) zmax = max3f(zmax, s1[1 + 2 * k], s1[2 + 2 * k]);
;   zmax = fmaxf(zmax, s1[15]);
; #pragma unroll
;   for (int i = 0; i < 16; ++i) { s0[i] = __builtin_amdgcn_exp2f(s0[i]); s1[i] = __builtin_amdgcn_exp2f(s1[i]); }
;   if (__any((zmax + boff > st.m + DEFER_THR) || (st.m != boff))) {
;     const float zt = max32(zmax) + boff; const bool need = zt > st.m + DEFER_THR;
;     const float mn = need ? zt : st.m, alpha = __builtin_amdgcn_exp2f(st.m - mn), f = __builtin_amdgcn_exp2f(__builtin_fminf(boff - mn, 120.f)); st.m = mn;
; #pragma unroll
;     for (int i = 0; i < 16; ++i) { s0[i] *= f; s1[i] *= f; st.o0[i] *= alpha; st.o1[i] *= alpha; }
;     st.l *= alpha;
; template <int MODE, bool lookup, int MK>
; __device__ __forceinline__ void softmax_pv(f32x16& s0, f32x16& s1, SM& st, float boff, ldsp_t vb, LAS const float* tab, int t, int e_q, int posq, int hh, int r, bool mask_rt, float negv) {
;     ...
;       for (int i = 0; i < 16; ++i) { const int ek = ekb + (i & 7) + 16 * (i >> 3); int n0 = posq - (ek - koff), n1 = n0 - 32; n0 = (int)min((unsigned)n0, 128u); n1 = (int)min((unsigned)n1, 128u); s0[i] += tab[n0]; s1[i] += tab[n1]; }
	v_add_f32_e32 v69, v51, v69
	v_lshl_add_u32 v83, v83, 2, 0
	v_lshl_add_u32 v84, v84, 2, 0
	v_lshl_add_u32 v85, v85, 2, 0
	v_lshl_add_u32 v86, v86, 2, 0
	v_lshl_add_u32 v87, v87, 2, 0
	v_lshl_add_u32 v88, v88, 2, 0
	v_lshl_add_u32 v89, v89, 2, 0
	v_lshl_add_u32 v90, v90, 2, 0
	v_subrev_u32_e32 v92, 32, v91
	v_subrev_u32_e32 v94, 32, v93
	v_subrev_u32_e32 v96, 32, v95
	v_subrev_u32_e32 v97, 32, v66
	s_waitcnt lgkmcnt(11)
	v_add_f32_e32 v71, v52, v71
	s_waitcnt lgkmcnt(9)
	v_add_f32_e32 v73, v53, v73
	ds_read_b32 v83, v83 offset:57344
	ds_read_b32 v84, v84 offset:57344
	ds_read_b32 v85, v85 offset:57344
	ds_read_b32 v86, v86 offset:57344
	ds_read_b32 v87, v87 offset:57344
	ds_read_b32 v88, v88 offset:57344
	ds_read_b32 v89, v89 offset:57344
	ds_read_b32 v90, v90 offset:57344
	v_min_u32_e32 v91, 0x80, v91
	v_min_u32_e32 v92, 0x80, v92
	v_min_u32_e32 v93, 0x80, v93
	v_min_u32_e32 v94, 0x80, v94
	v_min_u32_e32 v95, 0x80, v95
	v_min_u32_e32 v96, 0x80, v96
	v_min_u32_e32 v66, 0x80, v66
	v_min_u32_e32 v97, 0x80, v97
	v_max_f32_e32 v156, v67, v69
	s_waitcnt lgkmcnt(14)
	v_add_f32_e32 v75, v54, v75
	s_waitcnt lgkmcnt(13)
	v_add_f32_e32 v77, v55, v77
	v_lshl_add_u32 v91, v91, 2, 0
	v_lshl_add_u32 v92, v92, 2, 0
	v_lshl_add_u32 v93, v93, 2, 0
	v_lshl_add_u32 v94, v94, 2, 0
	v_lshl_add_u32 v95, v95, 2, 0
	v_lshl_add_u32 v96, v96, 2, 0
	v_lshl_add_u32 v66, v66, 2, 0
	v_lshl_add_u32 v97, v97, 2, 0
	v_max3_f32 v156, v156, v71, v73
	s_waitcnt lgkmcnt(11)
	v_add_f32_e32 v79, v56, v79
	s_waitcnt lgkmcnt(9)
	v_add_f32_e32 v81, v57, v81
	ds_read_b32 v91, v91 offset:57344
	ds_read_b32 v92, v92 offset:57344
	ds_read_b32 v93, v93 offset:57344
	ds_read_b32 v94, v94 offset:57344
	ds_read_b32 v95, v95 offset:57344
	ds_read_b32 v96, v96 offset:57344
	ds_read_b32 v66, v66 offset:57344
	ds_read_b32 v97, v97 offset:57344
	v_max3_f32 v156, v156, v75, v77
	s_waitcnt lgkmcnt(14)
	v_add_f32_e32 v83, v58, v83
	s_waitcnt lgkmcnt(13)
	v_add_f32_e32 v85, v59, v85
	v_max3_f32 v156, v156, v79, v81
	s_waitcnt lgkmcnt(11)
	v_add_f32_e32 v87, v60, v87
	s_waitcnt lgkmcnt(9)
	v_add_f32_e32 v89, v61, v89
	v_max3_f32 v156, v156, v83, v85
	s_waitcnt lgkmcnt(7)
	v_add_f32_e32 v91, v62, v91
	s_waitcnt lgkmcnt(5)
	v_add_f32_e32 v93, v63, v93
	v_max3_f32 v156, v156, v87, v89
	s_waitcnt lgkmcnt(3)
	v_add_f32_e32 v95, v64, v95
	s_waitcnt lgkmcnt(1)
	v_add_f32_e32 v66, v65, v66
	v_max3_f32 v156, v156, v91, v93
	v_add_f32_e32 v68, v34, v68
	v_add_f32_e32 v70, v35, v70
	v_add3_u32 v122, s4, v224, v0
	v_max3_f32 v156, v156, v95, v66
	v_add_f32_e32 v72, v36, v72
	v_add_f32_e32 v74, v37, v74
	ds_read_b128 v[146:149], v122 offset:20480
	ds_read_b128 v[142:145], v122 offset:20512
	ds_read_b128 v[150:153], v122 offset:25088
	ds_read_b128 v[138:141], v122 offset:25120
	ds_read_b128 v[134:137], v122 offset:20544
	ds_read_b128 v[126:129], v122 offset:20576
	ds_read_b128 v[130:133], v122 offset:25152
	ds_read_b128 v[122:125], v122 offset:25184
	v_max3_f32 v156, v156, v68, v70
	v_add_f32_e32 v76, v38, v76
	v_add_f32_e32 v78, v39, v78
	v_max3_f32 v156, v156, v72, v74
	v_add_f32_e32 v80, v40, v80
	v_add_f32_e32 v82, v41, v82
	v_max3_f32 v156, v156, v76, v78
	v_add_f32_e32 v84, v42, v84
	v_add_f32_e32 v86, v43, v86
	v_max3_f32 v156, v156, v80, v82
	v_add_f32_e32 v88, v44, v88
	v_add_f32_e32 v90, v45, v90
	v_max3_f32 v156, v156, v84, v86
	v_add_f32_e32 v92, v46, v92
	v_add_f32_e32 v94, v47, v94
	v_max3_f32 v156, v156, v88, v90
	v_add_f32_e32 v96, v48, v96
	s_waitcnt lgkmcnt(8)
	v_add_f32_e32 v97, v49, v97
	v_max3_f32 v156, v156, v92, v94
	v_exp_f32_e32 v204, v67
	v_exp_f32_e32 v182, v68
	v_exp_f32_e32 v205, v69
	v_exp_f32_e32 v183, v70
	v_exp_f32_e32 v206, v71
	v_exp_f32_e32 v192, v72
	v_exp_f32_e32 v207, v73
	v_exp_f32_e32 v193, v74
	v_exp_f32_e32 v208, v75
	v_exp_f32_e32 v202, v76
	v_exp_f32_e32 v209, v77
	v_exp_f32_e32 v203, v78
	v_exp_f32_e32 v194, v79
	v_exp_f32_e32 v198, v80
	v_exp_f32_e32 v195, v81
	v_exp_f32_e32 v199, v82
	v_exp_f32_e32 v200, v83
	v_exp_f32_e32 v178, v84
	v_exp_f32_e32 v201, v85
	v_exp_f32_e32 v179, v86
	v_exp_f32_e32 v196, v87
	v_exp_f32_e32 v188, v88
	v_exp_f32_e32 v197, v89
	v_exp_f32_e32 v189, v90
	v_exp_f32_e32 v180, v91
	v_exp_f32_e32 v184, v92
	v_exp_f32_e32 v181, v93
	v_exp_f32_e32 v185, v94
	v_exp_f32_e32 v186, v95
	v_exp_f32_e32 v190, v96
	v_exp_f32_e32 v187, v66
	v_exp_f32_e32 v191, v97
	v_max3_f32 v156, v156, v96, v97
	v_pk_add_f32 v[66:67], v[176:177], v[156:157]
	v_cmp_neq_f32_e64 s[2:3], v177, v176
	v_cmp_gt_f32_e32 vcc, v66, v67
	s_or_b64 vcc, s[2:3], vcc
	s_cbranch_vccz .LBB0_1285
	v_mov_b32_e32 v66, v210
	v_max_f32_e32 v68, v156, v156
	v_lshlrev_b32_e32 v66, 2, v66
	v_xor_b32_e32 v66, 0x80, v66
	ds_bpermute_b32 v66, v66, v156
	s_waitcnt lgkmcnt(0)
	v_max_f32_e32 v66, v66, v66
	v_max_f32_e32 v66, v68, v66
	v_add_f32_e32 v66, v176, v66
	v_cmp_gt_f32_e32 vcc, v66, v67
	s_nop 1
	v_cndmask_b32_e32 v156, v177, v66, vcc
	v_sub_f32_e32 v66, v176, v156
	v_min_f32_e32 v66, 0x42f00000, v66
	v_sub_f32_e32 v67, v177, v156
	v_exp_f32_e32 v66, v66
	v_exp_f32_e32 v158, v67
	v_pk_mul_f32 v[186:187], v[186:187], v[66:67] op_sel_hi:[1,0]
	v_pk_mul_f32 v[180:181], v[180:181], v[66:67] op_sel_hi:[1,0]
	v_pk_mul_f32 v[196:197], v[196:197], v[66:67] op_sel_hi:[1,0]
	v_pk_mul_f32 v[200:201], v[200:201], v[66:67] op_sel_hi:[1,0]
	v_pk_mul_f32 v[194:195], v[194:195], v[66:67] op_sel_hi:[1,0]
	v_pk_mul_f32 v[208:209], v[208:209], v[66:67] op_sel_hi:[1,0]
	v_pk_mul_f32 v[206:207], v[206:207], v[66:67] op_sel_hi:[1,0]
	v_pk_mul_f32 v[204:205], v[204:205], v[66:67] op_sel_hi:[1,0]
	v_pk_mul_f32 v[190:191], v[190:191], v[66:67] op_sel_hi:[1,0]
	v_pk_mul_f32 v[184:185], v[184:185], v[66:67] op_sel_hi:[1,0]
	v_pk_mul_f32 v[188:189], v[188:189], v[66:67] op_sel_hi:[1,0]
	v_pk_mul_f32 v[178:179], v[178:179], v[66:67] op_sel_hi:[1,0]
	v_pk_mul_f32 v[198:199], v[198:199], v[66:67] op_sel_hi:[1,0]
	v_pk_mul_f32 v[202:203], v[202:203], v[66:67] op_sel_hi:[1,0]
	v_pk_mul_f32 v[192:193], v[192:193], v[66:67] op_sel_hi:[1,0]
	v_pk_mul_f32 v[182:183], v[182:183], v[66:67] op_sel_hi:[1,0]
	v_pk_mul_f32 v[32:33], v[32:33], v[158:159] op_sel_hi:[1,0]
	v_pk_mul_f32 v[30:31], v[30:31], v[158:159] op_sel_hi:[1,0]
	v_pk_mul_f32 v[28:29], v[28:29], v[158:159] op_sel_hi:[1,0]
	v_pk_mul_f32 v[26:27], v[26:27], v[158:159] op_sel_hi:[1,0]
	v_pk_mul_f32 v[24:25], v[24:25], v[158:159] op_sel_hi:[1,0]
	v_pk_mul_f32 v[22:23], v[22:23], v[158:159] op_sel_hi:[1,0]
	v_pk_mul_f32 v[20:21], v[20:21], v[158:159] op_sel_hi:[1,0]
	v_pk_mul_f32 v[18:19], v[18:19], v[158:159] op_sel_hi:[1,0]
	v_pk_mul_f32 v[16:17], v[16:17], v[158:159] op_sel_hi:[1,0]
	v_pk_mul_f32 v[14:15], v[14:15], v[158:159] op_sel_hi:[1,0]
	v_pk_mul_f32 v[12:13], v[12:13], v[158:159] op_sel_hi:[1,0]
	v_pk_mul_f32 v[10:11], v[10:11], v[158:159] op_sel_hi:[1,0]
	v_pk_mul_f32 v[8:9], v[8:9], v[158:159] op_sel_hi:[1,0]
	v_pk_mul_f32 v[6:7], v[6:7], v[158:159] op_sel_hi:[1,0]
	v_pk_mul_f32 v[4:5], v[4:5], v[158:159] op_sel_hi:[1,0]
	v_pk_mul_f32 v[2:3], v[2:3], v[158:159] op_sel_hi:[1,0]
	v_mul_f32_e32 v229, v228, v158
	s_branch .LBB0_1286

; __device__ __forceinline__ unsigned cvt_pk_bf16(float lo, float hi) { const f32x2 v = {lo, hi}; return __builtin_bit_cast(unsigned, __builtin_convertvector(v, bf16v2)); }
; __device__ __forceinline__ void softmax_tile(f32x16& s0, f32x16& s1, SM& st, float boff, ldsp_t vb, int hh, int r) {
;     ...
;   float ls = 0.f;
; #pragma unroll
;   for (int i = 0; i < 16; ++i) ls += s0[i] + s1[i];
;   st.l += ls;
;   bf16x8 pf[2][2];
; #pragma unroll
;   for (int s2 = 0; s2 < 2; ++s2) {
;     u32x4 w0, w1;
;     w0.x = cvt_pk_bf16(s0[8 * s2 + 0], s0[8 * s2 + 1]); w0.y = cvt_pk_bf16(s0[8 * s2 + 2], s0[8 * s2 + 3]); w0.z = cvt_pk_bf16(s0[8 * s2 + 4], s0[8 * s2 + 5]); w0.w = cvt_pk_bf16(s0[8 * s2 + 6], s0[8 * s2 + 7]);
;     w1.x = cvt_pk_bf16(s1[8 * s2 + 0], s1[8 * s2 + 1]); w1.y = cvt_pk_bf16(s1[8 * s2 + 2], s1[8 * s2 + 3]); w1.z = cvt_pk_bf16(s1[8 * s2 + 4], s1[8 * s2 + 5]); w1.w = cvt_pk_bf16(s1[8 * s2 + 6], s1[8 * s2 + 7]);
;     pf[0][s2] = __builtin_bit_cast(bf16x8, w0); pf[1][s2] = __builtin_bit_cast(bf16x8, w1);
;   }
; #pragma unroll
;   for (int kb = 0; kb < 2; ++kb)
; #pragma unroll
;     for (int s2 = 0; s2 < 2; ++s2) {
;       st.o0 = __builtin_amdgcn_mfma_f32_32x32x16_bf16(va0[kb][s2], pf[kb][s2], st.o0, 0, 0, 0);
;       st.o1 = __builtin_amdgcn_mfma_f32_32x32x16_bf16(va1[kb][s2], pf[kb][s2], st.o1, 0, 0, 0);
;     }
.LBB0_1286:
	v_cvt_pk_bf16_f32 v158, v204, v205
	v_cvt_pk_bf16_f32 v159, v206, v207
	v_cvt_pk_bf16_f32 v160, v208, v209
	v_cvt_pk_bf16_f32 v161, v194, v195
	s_waitcnt lgkmcnt(7)
	s_nop 0
	v_mfma_f32_32x32x16_bf16 v[18:33], v[146:149], v[158:161], v[18:33]
	v_cvt_pk_bf16_f32 v146, v200, v201
	v_cvt_pk_bf16_f32 v147, v196, v197
	v_cvt_pk_bf16_f32 v148, v180, v181
	v_cvt_pk_bf16_f32 v149, v186, v187
	s_waitcnt lgkmcnt(5)
	v_mfma_f32_32x32x16_bf16 v[2:17], v[150:153], v[158:161], v[2:17]
	v_mfma_f32_32x32x16_bf16 v[18:33], v[142:145], v[146:149], v[18:33]
	v_add_f32_e32 v142, v204, v182
	v_add_f32_e32 v142, 0, v142
	v_add_f32_e32 v143, v205, v183
	v_add_f32_e32 v142, v143, v142
	v_add_f32_e32 v143, v206, v192
	v_add_f32_e32 v142, v143, v142
	v_add_f32_e32 v143, v207, v193
	s_waitcnt lgkmcnt(4)
	v_mfma_f32_32x32x16_bf16 v[2:17], v[138:141], v[146:149], v[2:17]
	v_add_f32_e32 v138, v143, v142
	v_add_f32_e64 v142, v208, v202
	v_add_f32_e64 v143, v209, v203
	v_cvt_pk_bf16_f32 v139, v192, v193
	v_add_f32_e32 v142, v142, v138
	v_cvt_pk_bf16_f32 v138, v182, v183
	v_cvt_pk_bf16_f32 v140, v202, v203
	v_cvt_pk_bf16_f32 v141, v198, v199
	s_waitcnt lgkmcnt(3)
	s_nop 0
	v_mfma_f32_32x32x16_bf16 v[18:33], v[134:137], v[138:141], v[18:33]
	v_add_f32_e32 v136, v143, v142
	v_add_f32_e64 v134, v194, v198
	v_add_f32_e64 v135, v195, v199
	v_add_f32_e32 v134, v134, v136
	v_add_f32_e32 v136, v135, v134
	v_pk_add_f32 v[134:135], v[200:201], v[178:179]
	s_nop 0
	v_add_f32_e32 v134, v134, v136
	v_add_f32_e32 v134, v135, v134
	s_waitcnt lgkmcnt(1)
	v_mfma_f32_32x32x16_bf16 v[2:17], v[130:133], v[138:141], v[2:17]
	v_add_f32_e64 v130, v196, v188
	v_add_f32_e64 v131, v197, v189
	v_cvt_pk_bf16_f32 v132, v184, v185
	v_add_f32_e32 v130, v130, v134
	v_add_f32_e32 v134, v131, v130
	v_cvt_pk_bf16_f32 v130, v178, v179
	v_cvt_pk_bf16_f32 v131, v188, v189
	v_cvt_pk_bf16_f32 v133, v190, v191
	s_nop 1
	v_mfma_f32_32x32x16_bf16 v[18:33], v[126:129], v[130:133], v[18:33]
	v_add_f32_e64 v126, v180, v184
	v_add_f32_e64 v127, v181, v185
	v_add_f32_e32 v126, v126, v134
	v_add_f32_e32 v128, v127, v126
	v_add_f32_e64 v126, v186, v190
	v_add_f32_e64 v127, v187, v191
	v_add_f32_e32 v126, v126, v128
	v_add_f32_e32 v126, v127, v126
	v_add_f32_e32 v126, v229, v126
	s_waitcnt lgkmcnt(0)
	v_mfma_f32_32x32x16_bf16 v[2:17], v[122:125], v[130:133], v[2:17]
	s_cbranch_execnz .LBB0_1249
	s_branch .LBB0_1283

; #define LAS __attribute__((address_space(3)))
; template <int MODE>
; __device__ __forceinline__ void attn_item(const Params& P, int layer, int b, int h, int map, int qb) {
;     ...
;   auto qk = [&](f32x16& s0, f32x16& s1, float& boff, int bufi, int t) {
;     const ldsp_t kbuf = lds + bufi * KBUF;
;     __builtin_amdgcn_s_setprio(1);
;     boff = sa.m > -1e29f ? sa.m : 0.f;
;     const float init = ((MODE == 1 && !lookf(t)) ? cfar : 0.f) - boff;
; #pragma unroll
;     for (int q = 0; q < 16; ++q) { s0[q] = init; s1[q] = init; }
; #pragma unroll
;     for (int s = 0; s < NST; ++s) {
;       const bf16x8 a0 = *(LAS const bf16x8*)(kbuf + pr * KSTR + s * 32 + hh * 16);
;       const bf16x8 a1 = *(LAS const bf16x8*)(kbuf + (32 + pr) * KSTR + s * 32 + hh * 16);
;       s0 = __builtin_amdgcn_mfma_f32_32x32x16_bf16(a0, qf[s], s0, 0, 0, 0);
;       s1 = __builtin_amdgcn_mfma_f32_32x32x16_bf16(a1, qf[s], s1, 0, 0, 0);
;     }
;     __builtin_amdgcn_sched_group_barrier(0x100, 4, 0);
; #pragma unroll
;     for (int s = 0; s < NST - 2; ++s) { __builtin_amdgcn_sched_group_barrier(0x8, 2, 0); __builtin_amdgcn_sched_group_barrier(0x100, 2, 0); }
;     __builtin_amdgcn_sched_group_barrier(0x8, 4, 0);
;     __builtin_amdgcn_s_setprio(0);
;   };
.LBB0_1309:
	s_and_b32 s43, s37, 2
	s_cmp_ge_u32 s37, s62
	s_cbranch_scc1 .LBB0_1316
	s_sub_i32 s2, s42, 63
	s_cmp_gt_i32 s2, s36
	s_cselect_b64 s[2:3], -1, 0
	s_or_b64 s[2:3], s[2:3], s[68:69]
	s_cmp_eq_u32 s37, 0
	v_cndmask_b32_e64 v0, 0, 1, s[2:3]
	v_cndmask_b32_e64 v2, 0, 1, s[68:69]
	s_cselect_b64 s[2:3], -1, 0
	v_cndmask_b32_e64 v0, v0, v2, s[2:3]
	v_and_b32_e32 v0, 1, v0
	v_cmp_eq_u32_e32 vcc, 1, v0
	s_cbranch_vccnz .LBB0_1316
	s_cmp_gt_i32 s42, s21
	s_cselect_b64 s[4:5], -1, 0
	s_or_b64 s[4:5], s[2:3], s[4:5]
	s_setprio 1
	s_mul_i32 s6, s43, 0x3400
	v_add_u32_e32 v0, s6, v188
	ds_read_b128 v[6:9], v0
	ds_read_b128 v[2:5], v0 offset:6656
	ds_read_b128 v[10:13], v0 offset:32
	ds_read_b128 v[128:131], v0 offset:6688
	ds_read_b128 v[132:135], v0 offset:64
	ds_read_b128 v[136:139], v0 offset:6720
	ds_read_b128 v[140:143], v0 offset:96
	ds_read_b128 v[144:147], v0 offset:6752
	ds_read_b128 v[232:235], v0 offset:128
	ds_read_b128 v[236:239], v0 offset:6784
	ds_read_b128 v[240:243], v0 offset:160
	ds_read_b128 v[244:247], v0 offset:6816
	v_cmp_lt_f32_e32 vcc, s87, v169
	s_nop 1
	v_cndmask_b32_e32 v168, 0, v169, vcc
	v_sub_f32_e32 v48, 0, v168
	v_mov_b32_e32 v49, v48
	v_mov_b32_e32 v50, v48
	v_mov_b32_e32 v51, v48
	v_mov_b32_e32 v52, v48
	v_mov_b32_e32 v53, v48
	v_mov_b32_e32 v54, v48
	v_mov_b32_e32 v55, v48
	v_mov_b32_e32 v56, v48
	v_mov_b32_e32 v57, v48
	v_mov_b32_e32 v58, v48
	v_mov_b32_e32 v59, v48
	v_mov_b32_e32 v60, v48
	v_mov_b32_e32 v61, v48
	v_mov_b32_e32 v62, v48
	v_mov_b32_e32 v63, v48
	s_waitcnt lgkmcnt(11)
	s_nop 0
	v_mfma_f32_32x32x16_bf16 v[64:79], v[6:9], v[84:87], v[48:63]
	s_waitcnt lgkmcnt(10)
	v_mfma_f32_32x32x16_bf16 v[48:63], v[2:5], v[84:87], v[48:63]
	s_waitcnt lgkmcnt(9)
	v_mfma_f32_32x32x16_bf16 v[64:79], v[10:13], v[80:83], v[64:79]
	s_waitcnt lgkmcnt(8)
	v_mfma_f32_32x32x16_bf16 v[48:63], v[128:131], v[80:83], v[48:63]
	s_waitcnt lgkmcnt(7)
	v_mfma_f32_32x32x16_bf16 v[64:79], v[132:135], v[92:95], v[64:79]
	s_waitcnt lgkmcnt(6)
	v_mfma_f32_32x32x16_bf16 v[48:63], v[136:139], v[92:95], v[48:63]
	s_waitcnt lgkmcnt(5)
	v_mfma_f32_32x32x16_bf16 v[64:79], v[140:143], v[88:91], v[64:79]
	s_waitcnt lgkmcnt(4)
	v_mfma_f32_32x32x16_bf16 v[48:63], v[144:147], v[88:91], v[48:63]
	s_waitcnt lgkmcnt(3)
	v_mfma_f32_32x32x16_bf16 v[64:79], v[232:235], v[100:103], v[64:79]
	s_waitcnt lgkmcnt(2)
	v_mfma_f32_32x32x16_bf16 v[48:63], v[236:239], v[100:103], v[48:63]
	s_waitcnt lgkmcnt(1)
	v_mfma_f32_32x32x16_bf16 v[64:79], v[240:243], v[96:99], v[64:79]
	s_waitcnt lgkmcnt(0)
	v_mfma_f32_32x32x16_bf16 v[48:63], v[244:247], v[96:99], v[48:63]
	s_setprio 0
	s_andn2_b64 vcc, exec, s[4:5]
	s_cbranch_vccnz .LBB0_1313
; template <int MODE, bool lookup, int MK>
; __device__ __forceinline__ void softmax_pv(f32x16& s0, f32x16& s1, SM& st, float boff, ldsp_t vb, LAS const float* tab, int t, int e_q, int posq, int hh, int r, bool mask_rt, float negv) {
;     ...
;   if (need_mask) {
; #pragma unroll
;     for (int i = 0; i < 16; ++i) { const int ek0 = ekb + (i & 7) + 16 * (i >> 3), ek1 = ek0 + 32;
;       const bool v0 = (ek0 <= e_q) && (ek0 < klim) && (MODE != 2 || t == 0 || (e_q - ek0 < 128));
;       const bool v1 = (ek1 <= e_q) && (ek1 < klim) && (MODE != 2 || t == 0 || (e_q - ek1 < 128));
;       s0[i] = v0 ? s0[i] : negv; s1[i] = v1 ? s1[i] : negv; }
;   }
	s_and_b64 s[2:3], s[2:3], exec
	v_add_u32_e32 v0, s42, v150
	s_cselect_b32 s48, 16, 0x7fffffff
	v_subrev_u32_e32 v2, 63, v0
	v_subrev_u32_e32 v3, 31, v0
	v_cmp_le_i32_e32 vcc, v2, v151
	v_cmp_gt_u32_e64 s[2:3], s48, v2
	s_and_b64 vcc, vcc, s[2:3]
	v_cmp_le_i32_e64 s[2:3], v3, v151
	v_cmp_gt_u32_e64 s[4:5], s48, v3
	s_and_b64 s[2:3], s[2:3], s[4:5]
	v_subrev_u32_e32 v3, 62, v0
	v_cndmask_b32_e32 v64, v187, v64, vcc
	v_cndmask_b32_e64 v48, v187, v48, s[2:3]
	v_subrev_u32_e32 v4, 30, v0
	v_cmp_lt_i32_e32 vcc, v2, v151
	v_cmp_gt_u32_e64 s[2:3], s48, v3
	s_and_b64 vcc, vcc, s[2:3]
	v_cmp_le_i32_e64 s[2:3], v4, v151
	v_cmp_gt_u32_e64 s[4:5], s48, v4
	s_and_b64 s[2:3], s[2:3], s[4:5]
	v_subrev_u32_e32 v2, 61, v0
	v_cndmask_b32_e32 v65, v187, v65, vcc
	v_cndmask_b32_e64 v49, v187, v49, s[2:3]
	v_subrev_u32_e32 v3, 29, v0
	v_cmp_le_i32_e32 vcc, v2, v151
	v_cmp_gt_u32_e64 s[2:3], s48, v2
	s_and_b64 vcc, vcc, s[2:3]
	v_cmp_le_i32_e64 s[2:3], v3, v151
	v_cmp_gt_u32_e64 s[4:5], s48, v3
	s_and_b64 s[2:3], s[2:3], s[4:5]
	v_subrev_u32_e32 v2, 60, v0
	v_cndmask_b32_e32 v66, v187, v66, vcc
	v_cndmask_b32_e64 v50, v187, v50, s[2:3]
	v_subrev_u32_e32 v3, 28, v0
	v_cmp_le_i32_e32 vcc, v2, v151
	v_cmp_gt_u32_e64 s[2:3], s48, v2
	s_and_b64 vcc, vcc, s[2:3]
	v_cmp_le_i32_e64 s[2:3], v3, v151
	v_cmp_gt_u32_e64 s[4:5], s48, v3
	s_and_b64 s[2:3], s[2:3], s[4:5]
	v_subrev_u32_e32 v2, 59, v0
	v_cndmask_b32_e32 v67, v187, v67, vcc
	v_cndmask_b32_e64 v51, v187, v51, s[2:3]
	v_subrev_u32_e32 v3, 27, v0
	v_cmp_le_i32_e32 vcc, v2, v151
	v_cmp_gt_u32_e64 s[2:3], s48, v2
	s_and_b64 vcc, vcc, s[2:3]
	v_cmp_le_i32_e64 s[2:3], v3, v151
	v_cmp_gt_u32_e64 s[4:5], s48, v3
	s_and_b64 s[2:3], s[2:3], s[4:5]
	v_subrev_u32_e32 v2, 58, v0
	v_cndmask_b32_e32 v68, v187, v68, vcc
	v_cndmask_b32_e64 v52, v187, v52, s[2:3]
	v_subrev_u32_e32 v3, 26, v0
	v_cmp_le_i32_e32 vcc, v2, v151
	v_cmp_gt_u32_e64 s[2:3], s48, v2
	s_and_b64 vcc, vcc, s[2:3]
	v_cmp_le_i32_e64 s[2:3], v3, v151
	v_cmp_gt_u32_e64 s[4:5], s48, v3
	s_and_b64 s[2:3], s[2:3], s[4:5]
	v_subrev_u32_e32 v2, 57, v0
	v_cndmask_b32_e32 v69, v187, v69, vcc
	v_cndmask_b32_e64 v53, v187, v53, s[2:3]
	v_subrev_u32_e32 v3, 25, v0
	v_cmp_le_i32_e32 vcc, v2, v151
	v_cmp_gt_u32_e64 s[2:3], s48, v2
	s_and_b64 vcc, vcc, s[2:3]
	v_cmp_le_i32_e64 s[2:3], v3, v151
	v_cmp_gt_u32_e64 s[4:5], s48, v3
	s_and_b64 s[2:3], s[2:3], s[4:5]
	v_subrev_u32_e32 v2, 56, v0
	v_cndmask_b32_e32 v70, v187, v70, vcc
	v_cndmask_b32_e64 v54, v187, v54, s[2:3]
	v_subrev_u32_e32 v3, 24, v0
	v_cmp_le_i32_e32 vcc, v2, v151
	v_cmp_gt_u32_e64 s[2:3], s48, v2
	s_and_b64 vcc, vcc, s[2:3]
	v_cmp_le_i32_e64 s[2:3], v3, v151
	v_cmp_gt_u32_e64 s[4:5], s48, v3
	s_and_b64 s[2:3], s[2:3], s[4:5]
	v_subrev_u32_e32 v2, 47, v0
	v_cndmask_b32_e32 v71, v187, v71, vcc
	v_cndmask_b32_e64 v55, v187, v55, s[2:3]
	v_add_u32_e32 v3, -15, v0
	v_cmp_le_i32_e32 vcc, v2, v151
	v_cmp_gt_u32_e64 s[2:3], s48, v2
	s_and_b64 vcc, vcc, s[2:3]
	v_cmp_le_i32_e64 s[2:3], v3, v151
	v_cmp_gt_u32_e64 s[4:5], s48, v3
	s_and_b64 s[2:3], s[2:3], s[4:5]
	v_subrev_u32_e32 v2, 46, v0
	v_cndmask_b32_e32 v72, v187, v72, vcc
	v_cndmask_b32_e64 v56, v187, v56, s[2:3]
	v_add_u32_e32 v3, -14, v0
	v_cmp_le_i32_e32 vcc, v2, v151
	v_cmp_gt_u32_e64 s[2:3], s48, v2
	s_and_b64 vcc, vcc, s[2:3]
	v_cmp_le_i32_e64 s[2:3], v3, v151
	v_cmp_gt_u32_e64 s[4:5], s48, v3
	s_and_b64 s[2:3], s[2:3], s[4:5]
	v_subrev_u32_e32 v2, 45, v0
	v_cndmask_b32_e32 v73, v187, v73, vcc
	v_cndmask_b32_e64 v57, v187, v57, s[2:3]
	v_add_u32_e32 v3, -13, v0
	v_cmp_le_i32_e32 vcc, v2, v151
	v_cmp_gt_u32_e64 s[2:3], s48, v2
	s_and_b64 vcc, vcc, s[2:3]
	v_cmp_le_i32_e64 s[2:3], v3, v151
	v_cmp_gt_u32_e64 s[4:5], s48, v3
	s_and_b64 s[2:3], s[2:3], s[4:5]
	v_subrev_u32_e32 v2, 44, v0
	v_cndmask_b32_e32 v74, v187, v74, vcc
	v_cndmask_b32_e64 v58, v187, v58, s[2:3]
	v_add_u32_e32 v3, -12, v0
	v_cmp_le_i32_e32 vcc, v2, v151
	v_cmp_gt_u32_e64 s[2:3], s48, v2
	s_and_b64 vcc, vcc, s[2:3]
	v_cmp_le_i32_e64 s[2:3], v3, v151
	v_cmp_gt_u32_e64 s[4:5], s48, v3
	s_and_b64 s[2:3], s[2:3], s[4:5]
	v_subrev_u32_e32 v2, 43, v0
	v_cndmask_b32_e32 v75, v187, v75, vcc
	v_cndmask_b32_e64 v59, v187, v59, s[2:3]
	v_add_u32_e32 v3, -11, v0
	v_cmp_le_i32_e32 vcc, v2, v151
	v_cmp_gt_u32_e64 s[2:3], s48, v2
	s_and_b64 vcc, vcc, s[2:3]
	v_cmp_le_i32_e64 s[2:3], v3, v151
	v_cmp_gt_u32_e64 s[4:5], s48, v3
	s_and_b64 s[2:3], s[2:3], s[4:5]
	v_subrev_u32_e32 v2, 42, v0
	v_cndmask_b32_e32 v76, v187, v76, vcc
	v_cndmask_b32_e64 v60, v187, v60, s[2:3]
	v_add_u32_e32 v3, -10, v0
	v_cmp_le_i32_e32 vcc, v2, v151
	v_cmp_gt_u32_e64 s[2:3], s48, v2
	s_and_b64 vcc, vcc, s[2:3]
	v_cmp_le_i32_e64 s[2:3], v3, v151
	v_cmp_gt_u32_e64 s[4:5], s48, v3
	s_and_b64 s[2:3], s[2:3], s[4:5]
	v_subrev_u32_e32 v2, 41, v0
	v_cndmask_b32_e32 v77, v187, v77, vcc
	v_cndmask_b32_e64 v61, v187, v61, s[2:3]
	v_add_u32_e32 v3, -9, v0
	v_cmp_le_i32_e32 vcc, v2, v151
	v_cmp_gt_u32_e64 s[2:3], s48, v2
	s_and_b64 vcc, vcc, s[2:3]
	v_cmp_le_i32_e64 s[2:3], v3, v151
	v_cmp_gt_u32_e64 s[4:5], s48, v3
	s_and_b64 s[2:3], s[2:3], s[4:5]
	v_subrev_u32_e32 v2, 40, v0
	v_cndmask_b32_e32 v78, v187, v78, vcc
	v_cndmask_b32_e64 v62, v187, v62, s[2:3]
	v_add_u32_e32 v0, -8, v0
	v_cmp_le_i32_e32 vcc, v2, v151
	v_cmp_gt_u32_e64 s[2:3], s48, v2
	s_and_b64 vcc, vcc, s[2:3]
	v_cmp_le_i32_e64 s[2:3], v0, v151
	v_cmp_gt_u32_e64 s[4:5], s48, v0
	s_and_b64 s[2:3], s[2:3], s[4:5]
	v_cndmask_b32_e32 v79, v187, v79, vcc
	v_cndmask_b32_e64 v63, v187, v63, s[2:3]

; #define LAS __attribute__((address_space(3)))
; template <int MODE>
; __device__ __forceinline__ void attn_item(const Params& P, int layer, int b, int h, int map, int qb) {
;     ...
;   auto issue = [&](Stage& st, int t) {
; #pragma unroll
;     for (int u = 0; u < NLK; ++u) { int c = tid + 512 * u; if (c >= NKC) c -= (NKC % 512 == 0 ? 512 : NKC % 512);
;       const int row = c / CPR, cc = c % CPR; st.k[u] = *(const u32x4*)(kp + (size_t)(64 * t + row) * KLD + cc * 8); }
;     { const int row = tid >> 3, cc = tid & 7; st.v = *(const u32x4*)(vp + (size_t)row * E + 64 * t + cc * 8); }
;   };
;   auto commit = [&](const Stage& st, int bufi) {
; #pragma unroll
;     for (int u = 0; u < NLK; ++u) { int c = tid + 512 * u; if (c >= NKC) c -= (NKC % 512 == 0 ? 512 : NKC % 512);
;       const int row = c / CPR, cc = c % CPR; *(LAS u32x4*)(lds + bufi * KBUF + row * KSTR + cc * 16) = st.k[u]; }
;     { const int row = tid >> 3, cc = tid & 7; *(LAS u32x4*)(lds + 4 * KBUF + bufi * VBUF + row * 144 + cc * 16) = st.v; }
;   };
;   auto tile_of = [&](int i) { return i == 0 ? 0 : tstart + i - 1; };
;   auto skipf = [&](int t) { bool sk = !active; if (t > 0) { if (64 * t > eq0 + 31) sk = true; if (MODE == 2 && eq0 - (64 * t + 63) >= 128) sk = true; } return sk; };
;   const int pr = (r & 0x13) | ((r & 4) << 1) | ((r & 8) >> 1);
;   auto lookf = [&](int t) { return MODE != 0 && (t == 0 || MODE == 2 || (eq0 - (64 * t + 63) < 128)); };
;   auto qk = [&](f32x16& s0, f32x16& s1, float& boff, int bufi, int t) {
;     const ldsp_t kbuf = lds + bufi * KBUF;
;     __builtin_amdgcn_s_setprio(1);
;     boff = sa.m > -1e29f ? sa.m : 0.f;
;     const float init = ((MODE == 1 && !lookf(t)) ? cfar : 0.f) - boff;
; #pragma unroll
;     for (int q = 0; q < 16; ++q) { s0[q] = init; s1[q] = init; }
; #pragma unroll
;     for (int s = 0; s < NST; ++s) {
;       const bf16x8 a0 = *(LAS const bf16x8*)(kbuf + pr * KSTR + s * 32 + hh * 16);
;       const bf16x8 a1 = *(LAS const bf16x8*)(kbuf + (32 + pr) * KSTR + s * 32 + hh * 16);
;       s0 = __builtin_amdgcn_mfma_f32_32x32x16_bf16(a0, qf[s], s0, 0, 0, 0);
;       s1 = __builtin_amdgcn_mfma_f32_32x32x16_bf16(a1, qf[s], s1, 0, 0, 0);
;     }
;     __builtin_amdgcn_sched_group_barrier(0x100, 4, 0);
; #pragma unroll
;     for (int s = 0; s < NST - 2; ++s) { __builtin_amdgcn_sched_group_barrier(0x8, 2, 0); __builtin_amdgcn_sched_group_barrier(0x100, 2, 0); }
.LBB0_1316:
	s_xor_b32 s2, s43, 2
	s_mul_i32 s3, s2, 0x3400
	s_add_i32 s3, s3, 0
	v_add3_u32 v0, s3, v182, v183
	s_waitcnt vmcnt(5)
	ds_write_b128 v0, v[108:111]
	v_add3_u32 v0, s3, v184, v185
	s_mulk_i32 s2, 0x2400
	s_waitcnt vmcnt(4)
	ds_write_b128 v0, v[104:107]
	v_add_u32_e32 v0, s2, v186
	s_add_i32 s2, s37, 4
	s_min_i32 s2, s2, s63
	s_lshl_b32 s90, s2, 6
	s_waitcnt vmcnt(3)
	ds_write_b128 v0, v[112:115] offset:53248
	v_add_u32_e32 v0, s90, v180
	v_mad_i64_i32 v[2:3], s[2:3], v0, s47, v[152:153]
	v_add_u32_e32 v0, s90, v181
	v_mad_i64_i32 v[4:5], s[2:3], v0, s47, v[166:167]
	global_load_dwordx4 v[108:111], v[2:3], off
	global_load_dwordx4 v[104:107], v[4:5], off
	v_lshl_add_u64 v[2:3], s[90:91], 1, v[148:149]
	global_load_dwordx4 v[112:115], v[2:3], off
	s_add_i32 s2, s37, 1
	s_cmp_ge_u32 s2, s62
	s_cbranch_scc1 .LBB0_1308
	s_add_i32 s2, s42, 1
	s_cmp_le_i32 s2, s36
	s_cselect_b64 s[2:3], -1, 0
	s_and_b64 s[2:3], s[2:3], s[40:41]
	s_andn2_b64 vcc, exec, s[2:3]
	s_cbranch_vccnz .LBB0_1308
	s_add_i32 s3, s42, 64
	s_or_b32 s2, s43, 1
	s_cmp_le_i32 s3, s21
	s_setprio 1
	s_mul_i32 s3, s2, 0x3400
	v_add_u32_e32 v0, s3, v188
	ds_read_b128 v[6:9], v0
	ds_read_b128 v[2:5], v0 offset:6656
	ds_read_b128 v[10:13], v0 offset:32
	ds_read_b128 v[128:131], v0 offset:6688
	ds_read_b128 v[132:135], v0 offset:64
	ds_read_b128 v[136:139], v0 offset:6720
	ds_read_b128 v[140:143], v0 offset:96
	ds_read_b128 v[144:147], v0 offset:6752
	ds_read_b128 v[232:235], v0 offset:128
	ds_read_b128 v[236:239], v0 offset:6784
	ds_read_b128 v[240:243], v0 offset:160
	ds_read_b128 v[244:247], v0 offset:6816
	v_cmp_lt_f32_e32 vcc, s87, v169
	s_nop 1
	v_cndmask_b32_e32 v168, 0, v169, vcc
	v_sub_f32_e32 v48, 0, v168
	v_mov_b32_e32 v49, v48
	v_mov_b32_e32 v50, v48
	v_mov_b32_e32 v51, v48
	v_mov_b32_e32 v52, v48
	v_mov_b32_e32 v53, v48
	v_mov_b32_e32 v54, v48
	v_mov_b32_e32 v55, v48
	v_mov_b32_e32 v56, v48
	v_mov_b32_e32 v57, v48
	v_mov_b32_e32 v58, v48
	v_mov_b32_e32 v59, v48
	v_mov_b32_e32 v60, v48
	v_mov_b32_e32 v61, v48
	v_mov_b32_e32 v62, v48
	v_mov_b32_e32 v63, v48
	s_waitcnt lgkmcnt(11)
	s_nop 0
	v_mfma_f32_32x32x16_bf16 v[64:79], v[6:9], v[84:87], v[48:63]
	s_waitcnt lgkmcnt(10)
	v_mfma_f32_32x32x16_bf16 v[48:63], v[2:5], v[84:87], v[48:63]
	s_waitcnt lgkmcnt(9)
	v_mfma_f32_32x32x16_bf16 v[64:79], v[10:13], v[80:83], v[64:79]
	s_waitcnt lgkmcnt(8)
	v_mfma_f32_32x32x16_bf16 v[48:63], v[128:131], v[80:83], v[48:63]
	s_waitcnt lgkmcnt(7)
	v_mfma_f32_32x32x16_bf16 v[64:79], v[132:135], v[92:95], v[64:79]
	s_waitcnt lgkmcnt(6)
	v_mfma_f32_32x32x16_bf16 v[48:63], v[136:139], v[92:95], v[48:63]
	s_waitcnt lgkmcnt(5)
	v_mfma_f32_32x32x16_bf16 v[64:79], v[140:143], v[88:91], v[64:79]
	s_waitcnt lgkmcnt(4)
	v_mfma_f32_32x32x16_bf16 v[48:63], v[144:147], v[88:91], v[48:63]
	s_waitcnt lgkmcnt(3)
	v_mfma_f32_32x32x16_bf16 v[64:79], v[232:235], v[100:103], v[64:79]
	s_waitcnt lgkmcnt(2)
	v_mfma_f32_32x32x16_bf16 v[48:63], v[236:239], v[100:103], v[48:63]
	s_waitcnt lgkmcnt(1)
	v_mfma_f32_32x32x16_bf16 v[64:79], v[240:243], v[96:99], v[64:79]
	s_waitcnt lgkmcnt(0)
	v_mfma_f32_32x32x16_bf16 v[48:63], v[244:247], v[96:99], v[48:63]
	s_setprio 0
	s_cbranch_scc1 .LBB0_1320
	v_add_u32_e32 v0, s42, v150
	v_add_u32_e32 v2, 1, v0
	v_add_u32_e32 v3, 33, v0
	v_cmp_gt_i32_e32 vcc, v2, v151
	s_nop 4
	v_cndmask_b32_e32 v64, v64, v187, vcc
	v_cmp_gt_i32_e32 vcc, v3, v151
	v_add_u32_e32 v3, 34, v0
	s_nop 0
	v_cndmask_b32_e32 v48, v48, v187, vcc
	v_cmp_lt_i32_e32 vcc, v2, v151
	v_add_u32_e32 v2, 3, v0
	s_nop 0
	v_cndmask_b32_e32 v65, v187, v65, vcc
	v_cmp_gt_i32_e32 vcc, v3, v151
	v_add_u32_e32 v3, 35, v0
	s_nop 0
	v_cndmask_b32_e32 v49, v49, v187, vcc
	v_cmp_gt_i32_e32 vcc, v2, v151
	v_add_u32_e32 v2, 4, v0
	s_nop 0
	v_cndmask_b32_e32 v66, v66, v187, vcc
	v_cmp_gt_i32_e32 vcc, v3, v151
	v_add_u32_e32 v3, 36, v0
	s_nop 0
	v_cndmask_b32_e32 v50, v50, v187, vcc
	v_cmp_gt_i32_e32 vcc, v2, v151
	v_add_u32_e32 v2, 5, v0
	s_nop 0
	v_cndmask_b32_e32 v67, v67, v187, vcc
	v_cmp_gt_i32_e32 vcc, v3, v151
	v_add_u32_e32 v3, 37, v0
	s_nop 0
	v_cndmask_b32_e32 v51, v51, v187, vcc
	v_cmp_gt_i32_e32 vcc, v2, v151
	v_add_u32_e32 v2, 6, v0
	s_nop 0
	v_cndmask_b32_e32 v68, v68, v187, vcc
	v_cmp_gt_i32_e32 vcc, v3, v151
	v_add_u32_e32 v3, 38, v0
	s_nop 0
	v_cndmask_b32_e32 v52, v52, v187, vcc
	v_cmp_gt_i32_e32 vcc, v2, v151
	v_add_u32_e32 v2, 7, v0
	s_nop 0
	v_cndmask_b32_e32 v69, v69, v187, vcc
	v_cmp_gt_i32_e32 vcc, v3, v151
	v_add_u32_e32 v3, 39, v0
	s_nop 0
	v_cndmask_b32_e32 v53, v53, v187, vcc
	v_cmp_gt_i32_e32 vcc, v2, v151
	v_add_u32_e32 v2, 8, v0
	s_nop 0
	v_cndmask_b32_e32 v70, v70, v187, vcc
	v_cmp_gt_i32_e32 vcc, v3, v151
	v_add_u32_e32 v3, 40, v0
	s_nop 0
	v_cndmask_b32_e32 v54, v54, v187, vcc
	v_cmp_gt_i32_e32 vcc, v2, v151
	v_add_u32_e32 v2, 17, v0
	s_nop 0
	v_cndmask_b32_e32 v71, v71, v187, vcc
	v_cmp_gt_i32_e32 vcc, v3, v151
	v_add_u32_e32 v3, 49, v0
	s_nop 0
	v_cndmask_b32_e32 v55, v55, v187, vcc
	v_cmp_gt_i32_e32 vcc, v2, v151
	v_add_u32_e32 v2, 18, v0
	s_nop 0
	v_cndmask_b32_e32 v72, v72, v187, vcc
	v_cmp_gt_i32_e32 vcc, v3, v151
	v_add_u32_e32 v3, 50, v0
	s_nop 0
	v_cndmask_b32_e32 v56, v56, v187, vcc
	v_cmp_gt_i32_e32 vcc, v2, v151
	v_add_u32_e32 v2, 19, v0
	s_nop 0
	v_cndmask_b32_e32 v73, v73, v187, vcc
	v_cmp_gt_i32_e32 vcc, v3, v151
	v_add_u32_e32 v3, 51, v0
	s_nop 0
	v_cndmask_b32_e32 v57, v57, v187, vcc
	v_cmp_gt_i32_e32 vcc, v2, v151
	v_add_u32_e32 v2, 20, v0
	s_nop 0
	v_cndmask_b32_e32 v74, v74, v187, vcc
	v_cmp_gt_i32_e32 vcc, v3, v151
	v_add_u32_e32 v3, 52, v0
	s_nop 0
	v_cndmask_b32_e32 v58, v58, v187, vcc
	v_cmp_gt_i32_e32 vcc, v2, v151
	v_add_u32_e32 v2, 21, v0
	s_nop 0
	v_cndmask_b32_e32 v75, v75, v187, vcc
	v_cmp_gt_i32_e32 vcc, v3, v151
	v_add_u32_e32 v3, 53, v0
	s_nop 0
	v_cndmask_b32_e32 v59, v59, v187, vcc
	v_cmp_gt_i32_e32 vcc, v2, v151
	v_add_u32_e32 v2, 22, v0
	s_nop 0
	v_cndmask_b32_e32 v76, v76, v187, vcc
	v_cmp_gt_i32_e32 vcc, v3, v151
	v_add_u32_e32 v3, 54, v0
	s_nop 0
	v_cndmask_b32_e32 v60, v60, v187, vcc
	v_cmp_gt_i32_e32 vcc, v2, v151
	v_add_u32_e32 v2, 23, v0
	s_nop 0
	v_cndmask_b32_e32 v77, v77, v187, vcc
	v_cmp_gt_i32_e32 vcc, v3, v151
	v_add_u32_e32 v3, 55, v0
	s_nop 0
	v_cndmask_b32_e32 v61, v61, v187, vcc
	v_cmp_gt_i32_e32 vcc, v2, v151
	v_add_u32_e32 v2, 24, v0
	v_add_u32_e32 v0, 56, v0
	v_cndmask_b32_e32 v78, v78, v187, vcc
	v_cmp_gt_i32_e32 vcc, v3, v151
	s_nop 1
	v_cndmask_b32_e32 v62, v62, v187, vcc
	v_cmp_gt_i32_e32 vcc, v2, v151
	s_nop 1
	v_cndmask_b32_e32 v79, v79, v187, vcc
	v_cmp_gt_i32_e32 vcc, v0, v151
	s_nop 1
	v_cndmask_b32_e32 v63, v63, v187, vcc
